# attention softmax with scalar v_fma/v_add/v_mul pairs instead of packed v_pk_* f32 (packed f32 is slow beside the partner wave's MFMAs)
# speedup vs baseline: 1.0058x; 1.0058x over previous
.Latt_compute:
	ds_read_b128 v[48:51], v72 offset:0
	ds_read_b128 v[52:55], v146 offset:0
	ds_read_b128 v[56:59], v72 offset:2048
	ds_read_b128 v[60:63], v146 offset:2048
	ds_read_b128 v[64:67], v72 offset:4096
	ds_read_b128 v[68:71], v146 offset:4096
	ds_read_b128 v[32:35], v72 offset:6144
	ds_read_b128 v[36:39], v146 offset:6144
	ds_read_b128 v[40:43], v72 offset:8192
	s_waitcnt lgkmcnt(8)
	v_mfma_f32_16x16x32_bf16 v[78:81], v[48:51], v[0:3], 0
	ds_read_b128 v[44:47], v146 offset:8192
	s_waitcnt lgkmcnt(8)
	v_mfma_f32_16x16x32_bf16 v[78:81], v[52:55], v[4:7], v[78:81]
	ds_read_b128 v[48:51], v72 offset:10240
	s_waitcnt lgkmcnt(8)
	v_mfma_f32_16x16x32_bf16 v[82:85], v[56:59], v[0:3], 0
	ds_read_b128 v[52:55], v146 offset:10240
	s_waitcnt lgkmcnt(8)
	v_mfma_f32_16x16x32_bf16 v[82:85], v[60:63], v[4:7], v[82:85]
	ds_read_b128 v[56:59], v72 offset:12288
	s_waitcnt lgkmcnt(8)
	v_mfma_f32_16x16x32_bf16 v[86:89], v[64:67], v[0:3], 0
	ds_read_b128 v[60:63], v146 offset:12288
	s_waitcnt lgkmcnt(8)
	v_mfma_f32_16x16x32_bf16 v[86:89], v[68:71], v[4:7], v[86:89]
	ds_read_b128 v[64:67], v72 offset:14336
	s_waitcnt lgkmcnt(8)
	v_mfma_f32_16x16x32_bf16 v[90:93], v[32:35], v[0:3], 0
	ds_read_b128 v[68:71], v146 offset:14336
	s_waitcnt lgkmcnt(8)
	v_mfma_f32_16x16x32_bf16 v[90:93], v[36:39], v[4:7], v[90:93]
	ds_read_b128 v[32:35], v72 offset:16384
	s_waitcnt lgkmcnt(8)
	v_mfma_f32_16x16x32_bf16 v[94:97], v[40:43], v[0:3], 0
	ds_read_b128 v[36:39], v146 offset:16384
	s_waitcnt lgkmcnt(8)
	v_mfma_f32_16x16x32_bf16 v[94:97], v[44:47], v[4:7], v[94:97]
	ds_read_b128 v[40:43], v72 offset:18432
	s_waitcnt lgkmcnt(8)
	v_mfma_f32_16x16x32_bf16 v[98:101], v[48:51], v[0:3], 0
	ds_read_b128 v[44:47], v146 offset:18432
	s_waitcnt lgkmcnt(8)
	v_mfma_f32_16x16x32_bf16 v[98:101], v[52:55], v[4:7], v[98:101]
	ds_read_b128 v[48:51], v72 offset:20480
	s_waitcnt lgkmcnt(8)
	v_mfma_f32_16x16x32_bf16 v[102:105], v[56:59], v[0:3], 0
	ds_read_b128 v[52:55], v146 offset:20480
	s_waitcnt lgkmcnt(8)
	v_mfma_f32_16x16x32_bf16 v[102:105], v[60:63], v[4:7], v[102:105]
	ds_read_b128 v[56:59], v72 offset:22528
	s_waitcnt lgkmcnt(8)
	v_mfma_f32_16x16x32_bf16 v[106:109], v[64:67], v[0:3], 0
	ds_read_b128 v[60:63], v146 offset:22528
	s_waitcnt lgkmcnt(8)
	v_mfma_f32_16x16x32_bf16 v[106:109], v[68:71], v[4:7], v[106:109]
	ds_read_b128 v[64:67], v72 offset:24576
	s_waitcnt lgkmcnt(8)
	v_mfma_f32_16x16x32_bf16 v[110:113], v[32:35], v[0:3], 0
	ds_read_b128 v[68:71], v146 offset:24576
	s_waitcnt lgkmcnt(8)
	v_mfma_f32_16x16x32_bf16 v[110:113], v[36:39], v[4:7], v[110:113]
	ds_read_b128 v[32:35], v72 offset:26624
	s_waitcnt lgkmcnt(8)
	v_mfma_f32_16x16x32_bf16 v[114:117], v[40:43], v[0:3], 0
	ds_read_b128 v[36:39], v146 offset:26624
	s_waitcnt lgkmcnt(8)
	v_mfma_f32_16x16x32_bf16 v[114:117], v[44:47], v[4:7], v[114:117]
	ds_read_b128 v[40:43], v72 offset:28672
	s_waitcnt lgkmcnt(8)
	v_mfma_f32_16x16x32_bf16 v[118:121], v[48:51], v[0:3], 0
	ds_read_b128 v[44:47], v146 offset:28672
	s_waitcnt lgkmcnt(8)
	v_mfma_f32_16x16x32_bf16 v[118:121], v[52:55], v[4:7], v[118:121]
	ds_read_b128 v[48:51], v72 offset:30720
	s_waitcnt lgkmcnt(8)
	v_mfma_f32_16x16x32_bf16 v[122:125], v[56:59], v[0:3], 0
	ds_read_b128 v[52:55], v146 offset:30720
	s_waitcnt lgkmcnt(8)
	v_mfma_f32_16x16x32_bf16 v[122:125], v[60:63], v[4:7], v[122:125]
	s_waitcnt lgkmcnt(7)
	v_mfma_f32_16x16x32_bf16 v[126:129], v[64:67], v[0:3], 0
	s_waitcnt lgkmcnt(6)
	v_mfma_f32_16x16x32_bf16 v[126:129], v[68:71], v[4:7], v[126:129]
	s_waitcnt lgkmcnt(5)
	v_mfma_f32_16x16x32_bf16 v[130:133], v[32:35], v[0:3], 0
	s_waitcnt lgkmcnt(4)
	v_mfma_f32_16x16x32_bf16 v[130:133], v[36:39], v[4:7], v[130:133]
	s_waitcnt lgkmcnt(3)
	v_mfma_f32_16x16x32_bf16 v[134:137], v[40:43], v[0:3], 0
	s_waitcnt lgkmcnt(2)
	v_mfma_f32_16x16x32_bf16 v[134:137], v[44:47], v[4:7], v[134:137]
	s_waitcnt lgkmcnt(1)
	v_mfma_f32_16x16x32_bf16 v[138:141], v[48:51], v[0:3], 0
	s_waitcnt lgkmcnt(0)
	v_mfma_f32_16x16x32_bf16 v[138:141], v[52:55], v[4:7], v[138:141]
	ds_read_b64 v[48:49], v73 offset:36864
	ds_read_b64 v[50:51], v73 offset:36896
	ds_read_b64 v[52:53], v73 offset:45312
	ds_read_b64 v[54:55], v73 offset:45344
	ds_read_b64 v[56:57], v73 offset:53760
	ds_read_b64 v[58:59], v73 offset:53792
	ds_read_b64 v[60:61], v73 offset:62208
	ds_read_b64 v[62:63], v73 offset:62240
	ds_read_b64 v[64:65], v73 offset:36928
	ds_read_b64 v[66:67], v73 offset:36960
	ds_read_b64 v[68:69], v73 offset:45376
	ds_read_b64 v[70:71], v73 offset:45408
	v_max3_f32 v36, v78, v79, v80
	v_max3_f32 v36, v36, v81, v82
	v_max3_f32 v36, v36, v83, v84
	v_max3_f32 v36, v36, v85, v86
	v_max3_f32 v36, v36, v87, v88
	v_max3_f32 v36, v36, v89, v90
	v_max3_f32 v36, v36, v91, v92
	v_max3_f32 v36, v36, v93, v94
	v_max3_f32 v36, v36, v95, v96
	v_max3_f32 v36, v36, v97, v98
	v_max3_f32 v36, v36, v99, v100
	v_max3_f32 v36, v36, v101, v102
	v_max3_f32 v36, v36, v103, v104
	v_max3_f32 v36, v36, v105, v106
	v_max3_f32 v36, v36, v107, v108
	v_max3_f32 v36, v36, v109, v110
	v_max3_f32 v36, v36, v111, v112
	v_max3_f32 v36, v36, v113, v114
	v_max3_f32 v36, v36, v115, v116
	v_max3_f32 v36, v36, v117, v118
	v_max3_f32 v36, v36, v119, v120
	v_max3_f32 v36, v36, v121, v122
	v_max3_f32 v36, v36, v123, v124
	v_max3_f32 v36, v36, v125, v126
	v_max3_f32 v36, v36, v127, v128
	v_max3_f32 v36, v36, v129, v130
	v_max3_f32 v36, v36, v131, v132
	v_max3_f32 v36, v36, v133, v134
	v_max3_f32 v36, v36, v135, v136
	v_max3_f32 v36, v36, v137, v138
	v_max3_f32 v36, v36, v139, v140
	v_max_f32_e32 v36, v36, v141
	v_mov_b32_e32 v37, v36
	s_nop 1
	v_permlane16_swap_b32_e32 v36, v37
	v_max_f32_e32 v36, v36, v37
	v_mov_b32_e32 v37, v36
	s_nop 1
	v_permlane32_swap_b32_e32 v36, v37
	v_max_f32_e32 v36, v36, v37
	v_mul_f32_e64 v38, v36, -v144
	v_mov_b32_e32 v40, 0
	v_mov_b32_e32 v41, 0
	v_mov_b32_e32 v39, v38
	v_fma_f32 v78, v78, v144, v38
	v_fma_f32 v79, v79, v144, v38
	v_fma_f32 v80, v80, v144, v38
	v_fma_f32 v81, v81, v144, v38
	v_exp_f32_e32 v78, v78
	v_exp_f32_e32 v79, v79
	v_exp_f32_e32 v80, v80
	v_exp_f32_e32 v81, v81
	v_fma_f32 v82, v82, v144, v38
	v_fma_f32 v83, v83, v144, v38
	v_fma_f32 v84, v84, v144, v38
	v_fma_f32 v85, v85, v144, v38
	v_exp_f32_e32 v82, v82
	v_exp_f32_e32 v83, v83
	v_exp_f32_e32 v84, v84
	v_exp_f32_e32 v85, v85
	v_add_f32_e32 v40, v40, v78
	v_add_f32_e32 v41, v41, v79
	v_add_f32_e32 v40, v40, v80
	v_add_f32_e32 v41, v41, v81
	v_fma_f32 v86, v86, v144, v38
	v_fma_f32 v87, v87, v144, v38
	v_fma_f32 v88, v88, v144, v38
	v_fma_f32 v89, v89, v144, v38
	v_exp_f32_e32 v86, v86
	v_exp_f32_e32 v87, v87
	v_exp_f32_e32 v88, v88
	v_exp_f32_e32 v89, v89
	v_add_f32_e32 v40, v40, v82
	v_add_f32_e32 v41, v41, v83
	v_add_f32_e32 v40, v40, v84
	v_add_f32_e32 v41, v41, v85
	v_fma_f32 v90, v90, v144, v38
	v_fma_f32 v91, v91, v144, v38
	v_fma_f32 v92, v92, v144, v38
	v_fma_f32 v93, v93, v144, v38
	v_exp_f32_e32 v90, v90
	v_exp_f32_e32 v91, v91
	v_exp_f32_e32 v92, v92
	v_exp_f32_e32 v93, v93
	v_add_f32_e32 v40, v40, v86
	v_add_f32_e32 v41, v41, v87
	v_add_f32_e32 v40, v40, v88
	v_add_f32_e32 v41, v41, v89
	v_fma_f32 v94, v94, v144, v38
	v_fma_f32 v95, v95, v144, v38
	v_fma_f32 v96, v96, v144, v38
	v_fma_f32 v97, v97, v144, v38
	v_exp_f32_e32 v94, v94
	v_exp_f32_e32 v95, v95
	v_exp_f32_e32 v96, v96
	v_exp_f32_e32 v97, v97
	v_add_f32_e32 v40, v40, v90
	v_add_f32_e32 v41, v41, v91
	v_add_f32_e32 v40, v40, v92
	v_add_f32_e32 v41, v41, v93
	v_fma_f32 v98, v98, v144, v38
	v_fma_f32 v99, v99, v144, v38
	v_fma_f32 v100, v100, v144, v38
	v_fma_f32 v101, v101, v144, v38
	v_exp_f32_e32 v98, v98
	v_exp_f32_e32 v99, v99
	v_exp_f32_e32 v100, v100
	v_exp_f32_e32 v101, v101
	v_add_f32_e32 v40, v40, v94
	v_add_f32_e32 v41, v41, v95
	v_add_f32_e32 v40, v40, v96
	v_add_f32_e32 v41, v41, v97
	v_fma_f32 v102, v102, v144, v38
	v_fma_f32 v103, v103, v144, v38
	v_fma_f32 v104, v104, v144, v38
	v_fma_f32 v105, v105, v144, v38
	v_exp_f32_e32 v102, v102
	v_exp_f32_e32 v103, v103
	v_exp_f32_e32 v104, v104
	v_exp_f32_e32 v105, v105
	v_add_f32_e32 v40, v40, v98
	v_add_f32_e32 v41, v41, v99
	v_add_f32_e32 v40, v40, v100
	v_add_f32_e32 v41, v41, v101
	v_fma_f32 v106, v106, v144, v38
	v_fma_f32 v107, v107, v144, v38
	v_fma_f32 v108, v108, v144, v38
	v_fma_f32 v109, v109, v144, v38
	v_exp_f32_e32 v106, v106
	v_exp_f32_e32 v107, v107
	v_exp_f32_e32 v108, v108
	v_exp_f32_e32 v109, v109
	v_add_f32_e32 v40, v40, v102
	v_add_f32_e32 v41, v41, v103
	v_add_f32_e32 v40, v40, v104
	v_add_f32_e32 v41, v41, v105
	v_fma_f32 v110, v110, v144, v38
	v_fma_f32 v111, v111, v144, v38
	v_fma_f32 v112, v112, v144, v38
	v_fma_f32 v113, v113, v144, v38
	v_exp_f32_e32 v110, v110
	v_exp_f32_e32 v111, v111
	v_exp_f32_e32 v112, v112
	v_exp_f32_e32 v113, v113
	v_add_f32_e32 v40, v40, v106
	v_add_f32_e32 v41, v41, v107
	v_add_f32_e32 v40, v40, v108
	v_add_f32_e32 v41, v41, v109
	v_fma_f32 v114, v114, v144, v38
	v_fma_f32 v115, v115, v144, v38
	v_fma_f32 v116, v116, v144, v38
	v_fma_f32 v117, v117, v144, v38
	v_exp_f32_e32 v114, v114
	v_exp_f32_e32 v115, v115
	v_exp_f32_e32 v116, v116
	v_exp_f32_e32 v117, v117
	v_add_f32_e32 v40, v40, v110
	v_add_f32_e32 v41, v41, v111
	v_add_f32_e32 v40, v40, v112
	v_add_f32_e32 v41, v41, v113
	v_fma_f32 v118, v118, v144, v38
	v_fma_f32 v119, v119, v144, v38
	v_fma_f32 v120, v120, v144, v38
	v_fma_f32 v121, v121, v144, v38
	v_exp_f32_e32 v118, v118
	v_exp_f32_e32 v119, v119
	v_exp_f32_e32 v120, v120
	v_exp_f32_e32 v121, v121
	v_add_f32_e32 v40, v40, v114
	v_add_f32_e32 v41, v41, v115
	v_add_f32_e32 v40, v40, v116
	v_add_f32_e32 v41, v41, v117
	v_fma_f32 v122, v122, v144, v38
	v_fma_f32 v123, v123, v144, v38
	v_fma_f32 v124, v124, v144, v38
	v_fma_f32 v125, v125, v144, v38
	v_exp_f32_e32 v122, v122
	v_exp_f32_e32 v123, v123
	v_exp_f32_e32 v124, v124
	v_exp_f32_e32 v125, v125
	v_add_f32_e32 v40, v40, v118
	v_add_f32_e32 v41, v41, v119
	v_add_f32_e32 v40, v40, v120
	v_add_f32_e32 v41, v41, v121
	v_fma_f32 v126, v126, v144, v38
	v_fma_f32 v127, v127, v144, v38
	v_fma_f32 v128, v128, v144, v38
	v_fma_f32 v129, v129, v144, v38
	v_exp_f32_e32 v126, v126
	v_exp_f32_e32 v127, v127
	v_exp_f32_e32 v128, v128
	v_exp_f32_e32 v129, v129
	v_add_f32_e32 v40, v40, v122
	v_add_f32_e32 v41, v41, v123
	v_add_f32_e32 v40, v40, v124
	v_add_f32_e32 v41, v41, v125
	v_fma_f32 v130, v130, v144, v38
	v_fma_f32 v131, v131, v144, v38
	v_fma_f32 v132, v132, v144, v38
	v_fma_f32 v133, v133, v144, v38
	v_exp_f32_e32 v130, v130
	v_exp_f32_e32 v131, v131
	v_exp_f32_e32 v132, v132
	v_exp_f32_e32 v133, v133
	v_add_f32_e32 v40, v40, v126
	v_add_f32_e32 v41, v41, v127
	v_add_f32_e32 v40, v40, v128
	v_add_f32_e32 v41, v41, v129
	v_fma_f32 v134, v134, v144, v38
	v_fma_f32 v135, v135, v144, v38
	v_fma_f32 v136, v136, v144, v38
	v_fma_f32 v137, v137, v144, v38
	v_exp_f32_e32 v134, v134
	v_exp_f32_e32 v135, v135
	v_exp_f32_e32 v136, v136
	v_exp_f32_e32 v137, v137
	v_add_f32_e32 v40, v40, v130
	v_add_f32_e32 v41, v41, v131
	v_add_f32_e32 v40, v40, v132
	v_add_f32_e32 v41, v41, v133
	v_fma_f32 v138, v138, v144, v38
	v_fma_f32 v139, v139, v144, v38
	v_fma_f32 v140, v140, v144, v38
	v_fma_f32 v141, v141, v144, v38
	v_exp_f32_e32 v138, v138
	v_exp_f32_e32 v139, v139
	v_exp_f32_e32 v140, v140
	v_exp_f32_e32 v141, v141
	v_add_f32_e32 v40, v40, v134
	v_add_f32_e32 v41, v41, v135
	v_add_f32_e32 v40, v40, v136
	v_add_f32_e32 v41, v41, v137
	s_nop 0
	v_add_f32_e32 v40, v40, v138
	v_add_f32_e32 v41, v41, v139
	v_add_f32_e32 v40, v40, v140
	v_add_f32_e32 v41, v41, v141
	v_add_f32_e32 v36, v40, v41
	v_mov_b32_e32 v37, v36
	s_nop 1
	v_permlane16_swap_b32_e32 v36, v37
	v_add_f32_e32 v36, v36, v37
	v_mov_b32_e32 v37, v36
	s_nop 1
	v_permlane32_swap_b32_e32 v36, v37
	v_add_f32_e32 v36, v36, v37
	v_rcp_f32_e32 v142, v36
	v_cvt_pk_bf16_f32 v78, v78, v79
	v_cvt_pk_bf16_f32 v79, v80, v81
	v_cvt_pk_bf16_f32 v80, v82, v83
	v_cvt_pk_bf16_f32 v81, v84, v85
	v_cvt_pk_bf16_f32 v86, v86, v87
	v_cvt_pk_bf16_f32 v87, v88, v89
	v_cvt_pk_bf16_f32 v88, v90, v91
	v_cvt_pk_bf16_f32 v89, v92, v93
	v_cvt_pk_bf16_f32 v94, v94, v95
	v_cvt_pk_bf16_f32 v95, v96, v97
	v_cvt_pk_bf16_f32 v96, v98, v99
	v_cvt_pk_bf16_f32 v97, v100, v101
	v_cvt_pk_bf16_f32 v102, v102, v103
	v_cvt_pk_bf16_f32 v103, v104, v105
	v_cvt_pk_bf16_f32 v104, v106, v107
	v_cvt_pk_bf16_f32 v105, v108, v109
	v_cvt_pk_bf16_f32 v110, v110, v111
	v_cvt_pk_bf16_f32 v111, v112, v113
	v_cvt_pk_bf16_f32 v112, v114, v115
	v_cvt_pk_bf16_f32 v113, v116, v117
	v_cvt_pk_bf16_f32 v118, v118, v119
	v_cvt_pk_bf16_f32 v119, v120, v121
	v_cvt_pk_bf16_f32 v120, v122, v123
	v_cvt_pk_bf16_f32 v121, v124, v125
	v_cvt_pk_bf16_f32 v126, v126, v127
	v_cvt_pk_bf16_f32 v127, v128, v129
	v_cvt_pk_bf16_f32 v128, v130, v131
	v_cvt_pk_bf16_f32 v129, v132, v133
	v_cvt_pk_bf16_f32 v134, v134, v135
	v_cvt_pk_bf16_f32 v135, v136, v137
	v_cvt_pk_bf16_f32 v136, v138, v139
	v_cvt_pk_bf16_f32 v137, v140, v141
	v_fma_f32 v143, -v36, v142, 1.0
	v_fma_f32 v142, v143, v142, v142
	v_mov_b32_e32 v143, v142
	ds_read_b64 v[82:83], v73 offset:53824
	ds_read_b64 v[84:85], v73 offset:53856
	s_waitcnt lgkmcnt(12)
	v_mfma_f32_16x16x32_bf16 v[32:35], v[48:51], v[78:81], 0
	ds_read_b64 v[90:91], v73 offset:62272
	ds_read_b64 v[92:93], v73 offset:62304
	s_waitcnt lgkmcnt(12)
	v_mfma_f32_16x16x32_bf16 v[36:39], v[52:55], v[78:81], 0
	ds_read_b64 v[48:49], v73 offset:36992
	ds_read_b64 v[50:51], v73 offset:37024
	s_waitcnt lgkmcnt(12)
	v_mfma_f32_16x16x32_bf16 v[40:43], v[56:59], v[78:81], 0
	ds_read_b64 v[52:53], v73 offset:45440
	ds_read_b64 v[54:55], v73 offset:45472
	s_waitcnt lgkmcnt(12)
	v_mfma_f32_16x16x32_bf16 v[44:47], v[60:63], v[78:81], 0
	ds_read_b64 v[56:57], v73 offset:53888
	ds_read_b64 v[58:59], v73 offset:53920
	s_waitcnt lgkmcnt(12)
	v_mfma_f32_16x16x32_bf16 v[32:35], v[64:67], v[86:89], v[32:35]
	ds_read_b64 v[60:61], v73 offset:62336
	ds_read_b64 v[62:63], v73 offset:62368
	s_waitcnt lgkmcnt(12)
	v_mfma_f32_16x16x32_bf16 v[36:39], v[68:71], v[86:89], v[36:39]
	ds_read_b64 v[64:65], v73 offset:37056
	ds_read_b64 v[66:67], v73 offset:37088
	s_waitcnt lgkmcnt(12)
	v_mfma_f32_16x16x32_bf16 v[40:43], v[82:85], v[86:89], v[40:43]
	ds_read_b64 v[68:69], v73 offset:45504
	ds_read_b64 v[70:71], v73 offset:45536
	s_waitcnt lgkmcnt(12)
	v_mfma_f32_16x16x32_bf16 v[44:47], v[90:93], v[86:89], v[44:47]
	ds_read_b64 v[82:83], v73 offset:53952
	ds_read_b64 v[84:85], v73 offset:53984
	s_waitcnt lgkmcnt(12)
	v_mfma_f32_16x16x32_bf16 v[32:35], v[48:51], v[94:97], v[32:35]
	ds_read_b64 v[90:91], v73 offset:62400
	ds_read_b64 v[92:93], v73 offset:62432
	s_waitcnt lgkmcnt(12)
	v_mfma_f32_16x16x32_bf16 v[36:39], v[52:55], v[94:97], v[36:39]
	ds_read_b64 v[48:49], v73 offset:37120
	ds_read_b64 v[50:51], v73 offset:37152
	s_waitcnt lgkmcnt(12)
	v_mfma_f32_16x16x32_bf16 v[40:43], v[56:59], v[94:97], v[40:43]
	ds_read_b64 v[52:53], v73 offset:45568
	ds_read_b64 v[54:55], v73 offset:45600
	s_waitcnt lgkmcnt(12)
	v_mfma_f32_16x16x32_bf16 v[44:47], v[60:63], v[94:97], v[44:47]
	ds_read_b64 v[56:57], v73 offset:54016
	ds_read_b64 v[58:59], v73 offset:54048
	s_waitcnt lgkmcnt(12)
	v_mfma_f32_16x16x32_bf16 v[32:35], v[64:67], v[102:105], v[32:35]
	ds_read_b64 v[60:61], v73 offset:62464
	ds_read_b64 v[62:63], v73 offset:62496
	s_waitcnt lgkmcnt(12)
	v_mfma_f32_16x16x32_bf16 v[36:39], v[68:71], v[102:105], v[36:39]
	ds_read_b64 v[64:65], v73 offset:37184
	ds_read_b64 v[66:67], v73 offset:37216
	s_waitcnt lgkmcnt(12)
	v_mfma_f32_16x16x32_bf16 v[40:43], v[82:85], v[102:105], v[40:43]
	ds_read_b64 v[68:69], v73 offset:45632
	ds_read_b64 v[70:71], v73 offset:45664
	s_waitcnt lgkmcnt(12)
	v_mfma_f32_16x16x32_bf16 v[44:47], v[90:93], v[102:105], v[44:47]
	ds_read_b64 v[82:83], v73 offset:54080
	ds_read_b64 v[84:85], v73 offset:54112
	s_waitcnt lgkmcnt(12)
	v_mfma_f32_16x16x32_bf16 v[32:35], v[48:51], v[110:113], v[32:35]
	ds_read_b64 v[90:91], v73 offset:62528
	ds_read_b64 v[92:93], v73 offset:62560
	s_waitcnt lgkmcnt(12)
	v_mfma_f32_16x16x32_bf16 v[36:39], v[52:55], v[110:113], v[36:39]
	ds_read_b64 v[48:49], v73 offset:37248
	ds_read_b64 v[50:51], v73 offset:37280
	s_waitcnt lgkmcnt(12)
	v_mfma_f32_16x16x32_bf16 v[40:43], v[56:59], v[110:113], v[40:43]
	ds_read_b64 v[52:53], v73 offset:45696
	ds_read_b64 v[54:55], v73 offset:45728
	s_waitcnt lgkmcnt(12)
	v_mfma_f32_16x16x32_bf16 v[44:47], v[60:63], v[110:113], v[44:47]
	ds_read_b64 v[56:57], v73 offset:54144
	ds_read_b64 v[58:59], v73 offset:54176
	s_waitcnt lgkmcnt(12)
	v_mfma_f32_16x16x32_bf16 v[32:35], v[64:67], v[118:121], v[32:35]
	ds_read_b64 v[60:61], v73 offset:62592
	ds_read_b64 v[62:63], v73 offset:62624
	s_waitcnt lgkmcnt(12)
	v_mfma_f32_16x16x32_bf16 v[36:39], v[68:71], v[118:121], v[36:39]
	ds_read_b64 v[64:65], v73 offset:37312
	ds_read_b64 v[66:67], v73 offset:37344
	s_waitcnt lgkmcnt(12)
	v_mfma_f32_16x16x32_bf16 v[40:43], v[82:85], v[118:121], v[40:43]
	ds_read_b64 v[68:69], v73 offset:45760
	ds_read_b64 v[70:71], v73 offset:45792
	s_waitcnt lgkmcnt(12)
	v_mfma_f32_16x16x32_bf16 v[44:47], v[90:93], v[118:121], v[44:47]
	ds_read_b64 v[82:83], v73 offset:54208
	ds_read_b64 v[84:85], v73 offset:54240
	s_waitcnt lgkmcnt(12)
	v_mfma_f32_16x16x32_bf16 v[32:35], v[48:51], v[126:129], v[32:35]
	ds_read_b64 v[90:91], v73 offset:62656
	ds_read_b64 v[92:93], v73 offset:62688
	s_waitcnt lgkmcnt(12)
	v_mfma_f32_16x16x32_bf16 v[36:39], v[52:55], v[126:129], v[36:39]
	s_waitcnt lgkmcnt(10)
	v_mfma_f32_16x16x32_bf16 v[40:43], v[56:59], v[126:129], v[40:43]
	s_waitcnt lgkmcnt(8)
	v_mfma_f32_16x16x32_bf16 v[44:47], v[60:63], v[126:129], v[44:47]
	s_waitcnt lgkmcnt(6)
	v_mfma_f32_16x16x32_bf16 v[32:35], v[64:67], v[134:137], v[32:35]
	s_waitcnt lgkmcnt(4)
	v_mfma_f32_16x16x32_bf16 v[36:39], v[68:71], v[134:137], v[36:39]
	s_waitcnt lgkmcnt(2)
	v_mfma_f32_16x16x32_bf16 v[40:43], v[82:85], v[134:137], v[40:43]
	s_waitcnt lgkmcnt(0)
	v_mfma_f32_16x16x32_bf16 v[44:47], v[90:93], v[134:137], v[44:47]
	ds_read_b128 v[48:51], v72 offset:0
	ds_read_b128 v[52:55], v146 offset:0
	ds_read_b128 v[56:59], v72 offset:2048
	ds_read_b128 v[60:63], v146 offset:2048
	ds_read_b128 v[64:67], v72 offset:4096
	ds_read_b128 v[68:71], v146 offset:4096
	s_add_u32 s16, s12, 0x0
	s_addc_u32 s17, s13, 0
	s_nop 7
	v_mul_f32_e32 v32, v32, v142
	v_mul_f32_e32 v33, v33, v142
	v_mul_f32_e32 v34, v34, v142
	v_mul_f32_e32 v35, v35, v142
	v_mul_f32_e32 v36, v36, v142
	v_mul_f32_e32 v37, v37, v142
	v_mul_f32_e32 v38, v38, v142
	v_mul_f32_e32 v39, v39, v142
	v_mul_f32_e32 v40, v40, v142
	v_mul_f32_e32 v41, v41, v142
	v_mul_f32_e32 v42, v42, v142
	v_mul_f32_e32 v43, v43, v142
	v_mul_f32_e32 v44, v44, v142
	v_mul_f32_e32 v45, v45, v142
	v_mul_f32_e32 v46, v46, v142
	v_mul_f32_e32 v47, v47, v142
	v_cvt_pk_bf16_f32 v32, v32, v33
	v_cvt_pk_bf16_f32 v33, v34, v35
	v_cvt_pk_bf16_f32 v36, v36, v37
	v_cvt_pk_bf16_f32 v37, v38, v39
	v_cvt_pk_bf16_f32 v40, v40, v41
	v_cvt_pk_bf16_f32 v41, v42, v43
	v_cvt_pk_bf16_f32 v44, v44, v45
	v_cvt_pk_bf16_f32 v45, v46, v47
	global_store_dwordx2 v74, v[32:33], s[16:17] offset:0
	global_store_dwordx2 v74, v[36:37], s[16:17] offset:32
	global_store_dwordx2 v74, v[40:41], s[16:17] offset:64
	global_store_dwordx2 v74, v[44:45], s[16:17] offset:96
	ds_read_b128 v[32:35], v72 offset:6144
	ds_read_b128 v[36:39], v146 offset:6144
	ds_read_b128 v[40:43], v72 offset:8192
	s_waitcnt lgkmcnt(8)
	v_mfma_f32_16x16x32_bf16 v[78:81], v[48:51], v[8:11], 0
	ds_read_b128 v[44:47], v146 offset:8192
	s_waitcnt lgkmcnt(8)
	v_mfma_f32_16x16x32_bf16 v[78:81], v[52:55], v[12:15], v[78:81]
	ds_read_b128 v[48:51], v72 offset:10240
	s_waitcnt lgkmcnt(8)
	v_mfma_f32_16x16x32_bf16 v[82:85], v[56:59], v[8:11], 0
	ds_read_b128 v[52:55], v146 offset:10240
	s_waitcnt lgkmcnt(8)
	v_mfma_f32_16x16x32_bf16 v[82:85], v[60:63], v[12:15], v[82:85]
	ds_read_b128 v[56:59], v72 offset:12288
	s_waitcnt lgkmcnt(8)
	v_mfma_f32_16x16x32_bf16 v[86:89], v[64:67], v[8:11], 0
	ds_read_b128 v[60:63], v146 offset:12288
	s_waitcnt lgkmcnt(8)
	v_mfma_f32_16x16x32_bf16 v[86:89], v[68:71], v[12:15], v[86:89]
	ds_read_b128 v[64:67], v72 offset:14336
	s_waitcnt lgkmcnt(8)
	v_mfma_f32_16x16x32_bf16 v[90:93], v[32:35], v[8:11], 0
	ds_read_b128 v[68:71], v146 offset:14336
	s_waitcnt lgkmcnt(8)
	v_mfma_f32_16x16x32_bf16 v[90:93], v[36:39], v[12:15], v[90:93]
	ds_read_b128 v[32:35], v72 offset:16384
	s_waitcnt lgkmcnt(8)
	v_mfma_f32_16x16x32_bf16 v[94:97], v[40:43], v[8:11], 0
	ds_read_b128 v[36:39], v146 offset:16384
	s_waitcnt lgkmcnt(8)
	v_mfma_f32_16x16x32_bf16 v[94:97], v[44:47], v[12:15], v[94:97]
	ds_read_b128 v[40:43], v72 offset:18432
	s_waitcnt lgkmcnt(8)
	v_mfma_f32_16x16x32_bf16 v[98:101], v[48:51], v[8:11], 0
	ds_read_b128 v[44:47], v146 offset:18432
	s_waitcnt lgkmcnt(8)
	v_mfma_f32_16x16x32_bf16 v[98:101], v[52:55], v[12:15], v[98:101]
	ds_read_b128 v[48:51], v72 offset:20480
	s_waitcnt lgkmcnt(8)
	v_mfma_f32_16x16x32_bf16 v[102:105], v[56:59], v[8:11], 0
	ds_read_b128 v[52:55], v146 offset:20480
	s_waitcnt lgkmcnt(8)
	v_mfma_f32_16x16x32_bf16 v[102:105], v[60:63], v[12:15], v[102:105]
	ds_read_b128 v[56:59], v72 offset:22528
	s_waitcnt lgkmcnt(8)
	v_mfma_f32_16x16x32_bf16 v[106:109], v[64:67], v[8:11], 0
	ds_read_b128 v[60:63], v146 offset:22528
	s_waitcnt lgkmcnt(8)
	v_mfma_f32_16x16x32_bf16 v[106:109], v[68:71], v[12:15], v[106:109]
	ds_read_b128 v[64:67], v72 offset:24576
	s_waitcnt lgkmcnt(8)
	v_mfma_f32_16x16x32_bf16 v[110:113], v[32:35], v[8:11], 0
	ds_read_b128 v[68:71], v146 offset:24576
	s_waitcnt lgkmcnt(8)
	v_mfma_f32_16x16x32_bf16 v[110:113], v[36:39], v[12:15], v[110:113]
	ds_read_b128 v[32:35], v72 offset:26624
	s_waitcnt lgkmcnt(8)
	v_mfma_f32_16x16x32_bf16 v[114:117], v[40:43], v[8:11], 0
	ds_read_b128 v[36:39], v146 offset:26624
	s_waitcnt lgkmcnt(8)
	v_mfma_f32_16x16x32_bf16 v[114:117], v[44:47], v[12:15], v[114:117]
	ds_read_b128 v[40:43], v72 offset:28672
	s_waitcnt lgkmcnt(8)
	v_mfma_f32_16x16x32_bf16 v[118:121], v[48:51], v[8:11], 0
	ds_read_b128 v[44:47], v146 offset:28672
	s_waitcnt lgkmcnt(8)
	v_mfma_f32_16x16x32_bf16 v[118:121], v[52:55], v[12:15], v[118:121]
	ds_read_b128 v[48:51], v72 offset:30720
	s_waitcnt lgkmcnt(8)
	v_mfma_f32_16x16x32_bf16 v[122:125], v[56:59], v[8:11], 0
	ds_read_b128 v[52:55], v146 offset:30720
	s_waitcnt lgkmcnt(8)
	v_mfma_f32_16x16x32_bf16 v[122:125], v[60:63], v[12:15], v[122:125]
	s_waitcnt lgkmcnt(7)
	v_mfma_f32_16x16x32_bf16 v[126:129], v[64:67], v[8:11], 0
	s_waitcnt lgkmcnt(6)
	v_mfma_f32_16x16x32_bf16 v[126:129], v[68:71], v[12:15], v[126:129]
	s_waitcnt lgkmcnt(5)
	v_mfma_f32_16x16x32_bf16 v[130:133], v[32:35], v[8:11], 0
	s_waitcnt lgkmcnt(4)
	v_mfma_f32_16x16x32_bf16 v[130:133], v[36:39], v[12:15], v[130:133]
	s_waitcnt lgkmcnt(3)
	v_mfma_f32_16x16x32_bf16 v[134:137], v[40:43], v[8:11], 0
	s_waitcnt lgkmcnt(2)
	v_mfma_f32_16x16x32_bf16 v[134:137], v[44:47], v[12:15], v[134:137]
	s_waitcnt lgkmcnt(1)
	v_mfma_f32_16x16x32_bf16 v[138:141], v[48:51], v[8:11], 0
	s_waitcnt lgkmcnt(0)
	v_mfma_f32_16x16x32_bf16 v[138:141], v[52:55], v[12:15], v[138:141]
	ds_read_b64 v[48:49], v73 offset:36864
	ds_read_b64 v[50:51], v73 offset:36896
	ds_read_b64 v[52:53], v73 offset:45312
	ds_read_b64 v[54:55], v73 offset:45344
	ds_read_b64 v[56:57], v73 offset:53760
	ds_read_b64 v[58:59], v73 offset:53792
	ds_read_b64 v[60:61], v73 offset:62208
	ds_read_b64 v[62:63], v73 offset:62240
	ds_read_b64 v[64:65], v73 offset:36928
	ds_read_b64 v[66:67], v73 offset:36960
	ds_read_b64 v[68:69], v73 offset:45376
	ds_read_b64 v[70:71], v73 offset:45408
	v_max3_f32 v36, v78, v79, v80
	v_max3_f32 v36, v36, v81, v82
	v_max3_f32 v36, v36, v83, v84
	v_max3_f32 v36, v36, v85, v86
	v_max3_f32 v36, v36, v87, v88
	v_max3_f32 v36, v36, v89, v90
	v_max3_f32 v36, v36, v91, v92
	v_max3_f32 v36, v36, v93, v94
	v_max3_f32 v36, v36, v95, v96
	v_max3_f32 v36, v36, v97, v98
	v_max3_f32 v36, v36, v99, v100
	v_max3_f32 v36, v36, v101, v102
	v_max3_f32 v36, v36, v103, v104
	v_max3_f32 v36, v36, v105, v106
	v_max3_f32 v36, v36, v107, v108
	v_max3_f32 v36, v36, v109, v110
	v_max3_f32 v36, v36, v111, v112
	v_max3_f32 v36, v36, v113, v114
	v_max3_f32 v36, v36, v115, v116
	v_max3_f32 v36, v36, v117, v118
	v_max3_f32 v36, v36, v119, v120
	v_max3_f32 v36, v36, v121, v122
	v_max3_f32 v36, v36, v123, v124
	v_max3_f32 v36, v36, v125, v126
	v_max3_f32 v36, v36, v127, v128
	v_max3_f32 v36, v36, v129, v130
	v_max3_f32 v36, v36, v131, v132
	v_max3_f32 v36, v36, v133, v134
	v_max3_f32 v36, v36, v135, v136
	v_max3_f32 v36, v36, v137, v138
	v_max3_f32 v36, v36, v139, v140
	v_max_f32_e32 v36, v36, v141
	v_mov_b32_e32 v37, v36
	s_nop 1
	v_permlane16_swap_b32_e32 v36, v37
	v_max_f32_e32 v36, v36, v37
	v_mov_b32_e32 v37, v36
	s_nop 1
	v_permlane32_swap_b32_e32 v36, v37
	v_max_f32_e32 v36, v36, v37
	v_mul_f32_e64 v38, v36, -v144
	v_mov_b32_e32 v40, 0
	v_mov_b32_e32 v41, 0
	v_mov_b32_e32 v39, v38
	v_fma_f32 v78, v78, v144, v38
	v_fma_f32 v79, v79, v144, v38
	v_fma_f32 v80, v80, v144, v38
	v_fma_f32 v81, v81, v144, v38
	v_exp_f32_e32 v78, v78
	v_exp_f32_e32 v79, v79
	v_exp_f32_e32 v80, v80
	v_exp_f32_e32 v81, v81
	v_fma_f32 v82, v82, v144, v38
	v_fma_f32 v83, v83, v144, v38
	v_fma_f32 v84, v84, v144, v38
	v_fma_f32 v85, v85, v144, v38
	v_exp_f32_e32 v82, v82
	v_exp_f32_e32 v83, v83
	v_exp_f32_e32 v84, v84
	v_exp_f32_e32 v85, v85
	v_add_f32_e32 v40, v40, v78
	v_add_f32_e32 v41, v41, v79
	v_add_f32_e32 v40, v40, v80
	v_add_f32_e32 v41, v41, v81
	v_fma_f32 v86, v86, v144, v38
	v_fma_f32 v87, v87, v144, v38
	v_fma_f32 v88, v88, v144, v38
	v_fma_f32 v89, v89, v144, v38
	v_exp_f32_e32 v86, v86
	v_exp_f32_e32 v87, v87
	v_exp_f32_e32 v88, v88
	v_exp_f32_e32 v89, v89
	v_add_f32_e32 v40, v40, v82
	v_add_f32_e32 v41, v41, v83
	v_add_f32_e32 v40, v40, v84
	v_add_f32_e32 v41, v41, v85
	v_fma_f32 v90, v90, v144, v38
	v_fma_f32 v91, v91, v144, v38
	v_fma_f32 v92, v92, v144, v38
	v_fma_f32 v93, v93, v144, v38
	v_exp_f32_e32 v90, v90
	v_exp_f32_e32 v91, v91
	v_exp_f32_e32 v92, v92
	v_exp_f32_e32 v93, v93
	v_add_f32_e32 v40, v40, v86
	v_add_f32_e32 v41, v41, v87
	v_add_f32_e32 v40, v40, v88
	v_add_f32_e32 v41, v41, v89
	v_fma_f32 v94, v94, v144, v38
	v_fma_f32 v95, v95, v144, v38
	v_fma_f32 v96, v96, v144, v38
	v_fma_f32 v97, v97, v144, v38
	v_exp_f32_e32 v94, v94
	v_exp_f32_e32 v95, v95
	v_exp_f32_e32 v96, v96
	v_exp_f32_e32 v97, v97
	v_add_f32_e32 v40, v40, v90
	v_add_f32_e32 v41, v41, v91
	v_add_f32_e32 v40, v40, v92
	v_add_f32_e32 v41, v41, v93
	v_fma_f32 v98, v98, v144, v38
	v_fma_f32 v99, v99, v144, v38
	v_fma_f32 v100, v100, v144, v38
	v_fma_f32 v101, v101, v144, v38
	v_exp_f32_e32 v98, v98
	v_exp_f32_e32 v99, v99
	v_exp_f32_e32 v100, v100
	v_exp_f32_e32 v101, v101
	v_add_f32_e32 v40, v40, v94
	v_add_f32_e32 v41, v41, v95
	v_add_f32_e32 v40, v40, v96
	v_add_f32_e32 v41, v41, v97
	v_fma_f32 v102, v102, v144, v38
	v_fma_f32 v103, v103, v144, v38
	v_fma_f32 v104, v104, v144, v38
	v_fma_f32 v105, v105, v144, v38
	v_exp_f32_e32 v102, v102
	v_exp_f32_e32 v103, v103
	v_exp_f32_e32 v104, v104
	v_exp_f32_e32 v105, v105
	v_add_f32_e32 v40, v40, v98
	v_add_f32_e32 v41, v41, v99
	v_add_f32_e32 v40, v40, v100
	v_add_f32_e32 v41, v41, v101
	v_fma_f32 v106, v106, v144, v38
	v_fma_f32 v107, v107, v144, v38
	v_fma_f32 v108, v108, v144, v38
	v_fma_f32 v109, v109, v144, v38
	v_exp_f32_e32 v106, v106
	v_exp_f32_e32 v107, v107
	v_exp_f32_e32 v108, v108
	v_exp_f32_e32 v109, v109
	v_add_f32_e32 v40, v40, v102
	v_add_f32_e32 v41, v41, v103
	v_add_f32_e32 v40, v40, v104
	v_add_f32_e32 v41, v41, v105
	v_fma_f32 v110, v110, v144, v38
	v_fma_f32 v111, v111, v144, v38
	v_fma_f32 v112, v112, v144, v38
	v_fma_f32 v113, v113, v144, v38
	v_exp_f32_e32 v110, v110
	v_exp_f32_e32 v111, v111
	v_exp_f32_e32 v112, v112
	v_exp_f32_e32 v113, v113
	v_add_f32_e32 v40, v40, v106
	v_add_f32_e32 v41, v41, v107
	v_add_f32_e32 v40, v40, v108
	v_add_f32_e32 v41, v41, v109
	v_fma_f32 v114, v114, v144, v38
	v_fma_f32 v115, v115, v144, v38
	v_fma_f32 v116, v116, v144, v38
	v_fma_f32 v117, v117, v144, v38
	v_exp_f32_e32 v114, v114
	v_exp_f32_e32 v115, v115
	v_exp_f32_e32 v116, v116
	v_exp_f32_e32 v117, v117
	v_add_f32_e32 v40, v40, v110
	v_add_f32_e32 v41, v41, v111
	v_add_f32_e32 v40, v40, v112
	v_add_f32_e32 v41, v41, v113
	v_fma_f32 v118, v118, v144, v38
	v_fma_f32 v119, v119, v144, v38
	v_fma_f32 v120, v120, v144, v38
	v_fma_f32 v121, v121, v144, v38
	v_exp_f32_e32 v118, v118
	v_exp_f32_e32 v119, v119
	v_exp_f32_e32 v120, v120
	v_exp_f32_e32 v121, v121
	v_add_f32_e32 v40, v40, v114
	v_add_f32_e32 v41, v41, v115
	v_add_f32_e32 v40, v40, v116
	v_add_f32_e32 v41, v41, v117
	v_fma_f32 v122, v122, v144, v38
	v_fma_f32 v123, v123, v144, v38
	v_fma_f32 v124, v124, v144, v38
	v_fma_f32 v125, v125, v144, v38
	v_exp_f32_e32 v122, v122
	v_exp_f32_e32 v123, v123
	v_exp_f32_e32 v124, v124
	v_exp_f32_e32 v125, v125
	v_add_f32_e32 v40, v40, v118
	v_add_f32_e32 v41, v41, v119
	v_add_f32_e32 v40, v40, v120
	v_add_f32_e32 v41, v41, v121
	v_fma_f32 v126, v126, v144, v38
	v_fma_f32 v127, v127, v144, v38
	v_fma_f32 v128, v128, v144, v38
	v_fma_f32 v129, v129, v144, v38
	v_exp_f32_e32 v126, v126
	v_exp_f32_e32 v127, v127
	v_exp_f32_e32 v128, v128
	v_exp_f32_e32 v129, v129
	v_add_f32_e32 v40, v40, v122
	v_add_f32_e32 v41, v41, v123
	v_add_f32_e32 v40, v40, v124
	v_add_f32_e32 v41, v41, v125
	v_fma_f32 v130, v130, v144, v38
	v_fma_f32 v131, v131, v144, v38
	v_fma_f32 v132, v132, v144, v38
	v_fma_f32 v133, v133, v144, v38
	v_exp_f32_e32 v130, v130
	v_exp_f32_e32 v131, v131
	v_exp_f32_e32 v132, v132
	v_exp_f32_e32 v133, v133
	v_add_f32_e32 v40, v40, v126
	v_add_f32_e32 v41, v41, v127
	v_add_f32_e32 v40, v40, v128
	v_add_f32_e32 v41, v41, v129
	v_fma_f32 v134, v134, v144, v38
	v_fma_f32 v135, v135, v144, v38
	v_fma_f32 v136, v136, v144, v38
	v_fma_f32 v137, v137, v144, v38
	v_exp_f32_e32 v134, v134
	v_exp_f32_e32 v135, v135
	v_exp_f32_e32 v136, v136
	v_exp_f32_e32 v137, v137
	v_add_f32_e32 v40, v40, v130
	v_add_f32_e32 v41, v41, v131
	v_add_f32_e32 v40, v40, v132
	v_add_f32_e32 v41, v41, v133
	v_fma_f32 v138, v138, v144, v38
	v_fma_f32 v139, v139, v144, v38
	v_fma_f32 v140, v140, v144, v38
	v_fma_f32 v141, v141, v144, v38
	v_exp_f32_e32 v138, v138
	v_exp_f32_e32 v139, v139
	v_exp_f32_e32 v140, v140
	v_exp_f32_e32 v141, v141
	v_add_f32_e32 v40, v40, v134
	v_add_f32_e32 v41, v41, v135
	v_add_f32_e32 v40, v40, v136
	v_add_f32_e32 v41, v41, v137
	s_nop 0
	v_add_f32_e32 v40, v40, v138
	v_add_f32_e32 v41, v41, v139
	v_add_f32_e32 v40, v40, v140
	v_add_f32_e32 v41, v41, v141
	v_add_f32_e32 v36, v40, v41
	v_mov_b32_e32 v37, v36
	s_nop 1
	v_permlane16_swap_b32_e32 v36, v37
	v_add_f32_e32 v36, v36, v37
	v_mov_b32_e32 v37, v36
	s_nop 1
	v_permlane32_swap_b32_e32 v36, v37
	v_add_f32_e32 v36, v36, v37
	v_rcp_f32_e32 v142, v36
	v_cvt_pk_bf16_f32 v78, v78, v79
	v_cvt_pk_bf16_f32 v79, v80, v81
	v_cvt_pk_bf16_f32 v80, v82, v83
	v_cvt_pk_bf16_f32 v81, v84, v85
	v_cvt_pk_bf16_f32 v86, v86, v87
	v_cvt_pk_bf16_f32 v87, v88, v89
	v_cvt_pk_bf16_f32 v88, v90, v91
	v_cvt_pk_bf16_f32 v89, v92, v93
	v_cvt_pk_bf16_f32 v94, v94, v95
	v_cvt_pk_bf16_f32 v95, v96, v97
	v_cvt_pk_bf16_f32 v96, v98, v99
	v_cvt_pk_bf16_f32 v97, v100, v101
	v_cvt_pk_bf16_f32 v102, v102, v103
	v_cvt_pk_bf16_f32 v103, v104, v105
	v_cvt_pk_bf16_f32 v104, v106, v107
	v_cvt_pk_bf16_f32 v105, v108, v109
	v_cvt_pk_bf16_f32 v110, v110, v111
	v_cvt_pk_bf16_f32 v111, v112, v113
	v_cvt_pk_bf16_f32 v112, v114, v115
	v_cvt_pk_bf16_f32 v113, v116, v117
	v_cvt_pk_bf16_f32 v118, v118, v119
	v_cvt_pk_bf16_f32 v119, v120, v121
	v_cvt_pk_bf16_f32 v120, v122, v123
	v_cvt_pk_bf16_f32 v121, v124, v125
	v_cvt_pk_bf16_f32 v126, v126, v127
	v_cvt_pk_bf16_f32 v127, v128, v129
	v_cvt_pk_bf16_f32 v128, v130, v131
	v_cvt_pk_bf16_f32 v129, v132, v133
	v_cvt_pk_bf16_f32 v134, v134, v135
	v_cvt_pk_bf16_f32 v135, v136, v137
	v_cvt_pk_bf16_f32 v136, v138, v139
	v_cvt_pk_bf16_f32 v137, v140, v141
	v_fma_f32 v143, -v36, v142, 1.0
	v_fma_f32 v142, v143, v142, v142
	v_mov_b32_e32 v143, v142
	ds_read_b64 v[82:83], v73 offset:53824
	ds_read_b64 v[84:85], v73 offset:53856
	s_waitcnt lgkmcnt(12)
	v_mfma_f32_16x16x32_bf16 v[32:35], v[48:51], v[78:81], 0
	ds_read_b64 v[90:91], v73 offset:62272
	ds_read_b64 v[92:93], v73 offset:62304
	s_waitcnt lgkmcnt(12)
	v_mfma_f32_16x16x32_bf16 v[36:39], v[52:55], v[78:81], 0
	ds_read_b64 v[48:49], v73 offset:36992
	ds_read_b64 v[50:51], v73 offset:37024
	s_waitcnt lgkmcnt(12)
	v_mfma_f32_16x16x32_bf16 v[40:43], v[56:59], v[78:81], 0
	ds_read_b64 v[52:53], v73 offset:45440
	ds_read_b64 v[54:55], v73 offset:45472
	s_waitcnt lgkmcnt(12)
	v_mfma_f32_16x16x32_bf16 v[44:47], v[60:63], v[78:81], 0
	ds_read_b64 v[56:57], v73 offset:53888
	ds_read_b64 v[58:59], v73 offset:53920
	s_waitcnt lgkmcnt(12)
	v_mfma_f32_16x16x32_bf16 v[32:35], v[64:67], v[86:89], v[32:35]
	ds_read_b64 v[60:61], v73 offset:62336
	ds_read_b64 v[62:63], v73 offset:62368
	s_waitcnt lgkmcnt(12)
	v_mfma_f32_16x16x32_bf16 v[36:39], v[68:71], v[86:89], v[36:39]
	ds_read_b64 v[64:65], v73 offset:37056
	ds_read_b64 v[66:67], v73 offset:37088
	s_waitcnt lgkmcnt(12)
	v_mfma_f32_16x16x32_bf16 v[40:43], v[82:85], v[86:89], v[40:43]
	ds_read_b64 v[68:69], v73 offset:45504
	ds_read_b64 v[70:71], v73 offset:45536
	s_waitcnt lgkmcnt(12)
	v_mfma_f32_16x16x32_bf16 v[44:47], v[90:93], v[86:89], v[44:47]
	ds_read_b64 v[82:83], v73 offset:53952
	ds_read_b64 v[84:85], v73 offset:53984
	s_waitcnt lgkmcnt(12)
	v_mfma_f32_16x16x32_bf16 v[32:35], v[48:51], v[94:97], v[32:35]
	ds_read_b64 v[90:91], v73 offset:62400
	ds_read_b64 v[92:93], v73 offset:62432
	s_waitcnt lgkmcnt(12)
	v_mfma_f32_16x16x32_bf16 v[36:39], v[52:55], v[94:97], v[36:39]
	ds_read_b64 v[48:49], v73 offset:37120
	ds_read_b64 v[50:51], v73 offset:37152
	s_waitcnt lgkmcnt(12)
	v_mfma_f32_16x16x32_bf16 v[40:43], v[56:59], v[94:97], v[40:43]
	ds_read_b64 v[52:53], v73 offset:45568
	ds_read_b64 v[54:55], v73 offset:45600
	s_waitcnt lgkmcnt(12)
	v_mfma_f32_16x16x32_bf16 v[44:47], v[60:63], v[94:97], v[44:47]
	ds_read_b64 v[56:57], v73 offset:54016
	ds_read_b64 v[58:59], v73 offset:54048
	s_waitcnt lgkmcnt(12)
	v_mfma_f32_16x16x32_bf16 v[32:35], v[64:67], v[102:105], v[32:35]
	ds_read_b64 v[60:61], v73 offset:62464
	ds_read_b64 v[62:63], v73 offset:62496
	s_waitcnt lgkmcnt(12)
	v_mfma_f32_16x16x32_bf16 v[36:39], v[68:71], v[102:105], v[36:39]
	ds_read_b64 v[64:65], v73 offset:37184
	ds_read_b64 v[66:67], v73 offset:37216
	s_waitcnt lgkmcnt(12)
	v_mfma_f32_16x16x32_bf16 v[40:43], v[82:85], v[102:105], v[40:43]
	ds_read_b64 v[68:69], v73 offset:45632
	ds_read_b64 v[70:71], v73 offset:45664
	s_waitcnt lgkmcnt(12)
	v_mfma_f32_16x16x32_bf16 v[44:47], v[90:93], v[102:105], v[44:47]
	ds_read_b64 v[82:83], v73 offset:54080
	ds_read_b64 v[84:85], v73 offset:54112
	s_waitcnt lgkmcnt(12)
	v_mfma_f32_16x16x32_bf16 v[32:35], v[48:51], v[110:113], v[32:35]
	ds_read_b64 v[90:91], v73 offset:62528
	ds_read_b64 v[92:93], v73 offset:62560
	s_waitcnt lgkmcnt(12)
	v_mfma_f32_16x16x32_bf16 v[36:39], v[52:55], v[110:113], v[36:39]
	ds_read_b64 v[48:49], v73 offset:37248
	ds_read_b64 v[50:51], v73 offset:37280
	s_waitcnt lgkmcnt(12)
	v_mfma_f32_16x16x32_bf16 v[40:43], v[56:59], v[110:113], v[40:43]
	ds_read_b64 v[52:53], v73 offset:45696
	ds_read_b64 v[54:55], v73 offset:45728
	s_waitcnt lgkmcnt(12)
	v_mfma_f32_16x16x32_bf16 v[44:47], v[60:63], v[110:113], v[44:47]
	ds_read_b64 v[56:57], v73 offset:54144
	ds_read_b64 v[58:59], v73 offset:54176
	s_waitcnt lgkmcnt(12)
	v_mfma_f32_16x16x32_bf16 v[32:35], v[64:67], v[118:121], v[32:35]
	ds_read_b64 v[60:61], v73 offset:62592
	ds_read_b64 v[62:63], v73 offset:62624
	s_waitcnt lgkmcnt(12)
	v_mfma_f32_16x16x32_bf16 v[36:39], v[68:71], v[118:121], v[36:39]
	ds_read_b64 v[64:65], v73 offset:37312
	ds_read_b64 v[66:67], v73 offset:37344
	s_waitcnt lgkmcnt(12)
	v_mfma_f32_16x16x32_bf16 v[40:43], v[82:85], v[118:121], v[40:43]
	ds_read_b64 v[68:69], v73 offset:45760
	ds_read_b64 v[70:71], v73 offset:45792
	s_waitcnt lgkmcnt(12)
	v_mfma_f32_16x16x32_bf16 v[44:47], v[90:93], v[118:121], v[44:47]
	ds_read_b64 v[82:83], v73 offset:54208
	ds_read_b64 v[84:85], v73 offset:54240
	s_waitcnt lgkmcnt(12)
	v_mfma_f32_16x16x32_bf16 v[32:35], v[48:51], v[126:129], v[32:35]
	ds_read_b64 v[90:91], v73 offset:62656
	ds_read_b64 v[92:93], v73 offset:62688
	s_waitcnt lgkmcnt(12)
	v_mfma_f32_16x16x32_bf16 v[36:39], v[52:55], v[126:129], v[36:39]
	s_waitcnt lgkmcnt(10)
	v_mfma_f32_16x16x32_bf16 v[40:43], v[56:59], v[126:129], v[40:43]
	s_waitcnt lgkmcnt(8)
	v_mfma_f32_16x16x32_bf16 v[44:47], v[60:63], v[126:129], v[44:47]
	s_waitcnt lgkmcnt(6)
	v_mfma_f32_16x16x32_bf16 v[32:35], v[64:67], v[134:137], v[32:35]
	s_waitcnt lgkmcnt(4)
	v_mfma_f32_16x16x32_bf16 v[36:39], v[68:71], v[134:137], v[36:39]
	s_waitcnt lgkmcnt(2)
	v_mfma_f32_16x16x32_bf16 v[40:43], v[82:85], v[134:137], v[40:43]
	s_waitcnt lgkmcnt(0)
	v_mfma_f32_16x16x32_bf16 v[44:47], v[90:93], v[134:137], v[44:47]
	ds_read_b128 v[48:51], v72 offset:0
	ds_read_b128 v[52:55], v146 offset:0
	ds_read_b128 v[56:59], v72 offset:2048
	ds_read_b128 v[60:63], v146 offset:2048
	ds_read_b128 v[64:67], v72 offset:4096
	ds_read_b128 v[68:71], v146 offset:4096
	s_add_u32 s16, s12, 0x8000
	s_addc_u32 s17, s13, 0
	s_nop 7
	v_mul_f32_e32 v32, v32, v142
	v_mul_f32_e32 v33, v33, v142
	v_mul_f32_e32 v34, v34, v142
	v_mul_f32_e32 v35, v35, v142
	v_mul_f32_e32 v36, v36, v142
	v_mul_f32_e32 v37, v37, v142
	v_mul_f32_e32 v38, v38, v142
	v_mul_f32_e32 v39, v39, v142
	v_mul_f32_e32 v40, v40, v142
	v_mul_f32_e32 v41, v41, v142
	v_mul_f32_e32 v42, v42, v142
	v_mul_f32_e32 v43, v43, v142
	v_mul_f32_e32 v44, v44, v142
	v_mul_f32_e32 v45, v45, v142
	v_mul_f32_e32 v46, v46, v142
	v_mul_f32_e32 v47, v47, v142
	v_cvt_pk_bf16_f32 v32, v32, v33
	v_cvt_pk_bf16_f32 v33, v34, v35
	v_cvt_pk_bf16_f32 v36, v36, v37
	v_cvt_pk_bf16_f32 v37, v38, v39
	v_cvt_pk_bf16_f32 v40, v40, v41
	v_cvt_pk_bf16_f32 v41, v42, v43
	v_cvt_pk_bf16_f32 v44, v44, v45
	v_cvt_pk_bf16_f32 v45, v46, v47
	global_store_dwordx2 v74, v[32:33], s[16:17] offset:0
	global_store_dwordx2 v74, v[36:37], s[16:17] offset:32
	global_store_dwordx2 v74, v[40:41], s[16:17] offset:64
	global_store_dwordx2 v74, v[44:45], s[16:17] offset:96
	ds_read_b128 v[32:35], v72 offset:6144
	ds_read_b128 v[36:39], v146 offset:6144
	ds_read_b128 v[40:43], v72 offset:8192
	s_waitcnt lgkmcnt(8)
	v_mfma_f32_16x16x32_bf16 v[78:81], v[48:51], v[16:19], 0
	ds_read_b128 v[44:47], v146 offset:8192
	s_waitcnt lgkmcnt(8)
	v_mfma_f32_16x16x32_bf16 v[78:81], v[52:55], v[20:23], v[78:81]
	ds_read_b128 v[48:51], v72 offset:10240
	s_waitcnt lgkmcnt(8)
	v_mfma_f32_16x16x32_bf16 v[82:85], v[56:59], v[16:19], 0
	ds_read_b128 v[52:55], v146 offset:10240
	s_waitcnt lgkmcnt(8)
	v_mfma_f32_16x16x32_bf16 v[82:85], v[60:63], v[20:23], v[82:85]
	ds_read_b128 v[56:59], v72 offset:12288
	s_waitcnt lgkmcnt(8)
	v_mfma_f32_16x16x32_bf16 v[86:89], v[64:67], v[16:19], 0
	ds_read_b128 v[60:63], v146 offset:12288
	s_waitcnt lgkmcnt(8)
	v_mfma_f32_16x16x32_bf16 v[86:89], v[68:71], v[20:23], v[86:89]
	ds_read_b128 v[64:67], v72 offset:14336
	s_waitcnt lgkmcnt(8)
	v_mfma_f32_16x16x32_bf16 v[90:93], v[32:35], v[16:19], 0
	ds_read_b128 v[68:71], v146 offset:14336
	s_waitcnt lgkmcnt(8)
	v_mfma_f32_16x16x32_bf16 v[90:93], v[36:39], v[20:23], v[90:93]
	ds_read_b128 v[32:35], v72 offset:16384
	s_waitcnt lgkmcnt(8)
	v_mfma_f32_16x16x32_bf16 v[94:97], v[40:43], v[16:19], 0
	ds_read_b128 v[36:39], v146 offset:16384
	s_waitcnt lgkmcnt(8)
	v_mfma_f32_16x16x32_bf16 v[94:97], v[44:47], v[20:23], v[94:97]
	ds_read_b128 v[40:43], v72 offset:18432
	s_waitcnt lgkmcnt(8)
	v_mfma_f32_16x16x32_bf16 v[98:101], v[48:51], v[16:19], 0
	ds_read_b128 v[44:47], v146 offset:18432
	s_waitcnt lgkmcnt(8)
	v_mfma_f32_16x16x32_bf16 v[98:101], v[52:55], v[20:23], v[98:101]
	ds_read_b128 v[48:51], v72 offset:20480
	s_waitcnt lgkmcnt(8)
	v_mfma_f32_16x16x32_bf16 v[102:105], v[56:59], v[16:19], 0
	ds_read_b128 v[52:55], v146 offset:20480
	s_waitcnt lgkmcnt(8)
	v_mfma_f32_16x16x32_bf16 v[102:105], v[60:63], v[20:23], v[102:105]
	ds_read_b128 v[56:59], v72 offset:22528
	s_waitcnt lgkmcnt(8)
	v_mfma_f32_16x16x32_bf16 v[106:109], v[64:67], v[16:19], 0
	ds_read_b128 v[60:63], v146 offset:22528
	s_waitcnt lgkmcnt(8)
	v_mfma_f32_16x16x32_bf16 v[106:109], v[68:71], v[20:23], v[106:109]
	ds_read_b128 v[64:67], v72 offset:24576
	s_waitcnt lgkmcnt(8)
	v_mfma_f32_16x16x32_bf16 v[110:113], v[32:35], v[16:19], 0
	ds_read_b128 v[68:71], v146 offset:24576
	s_waitcnt lgkmcnt(8)
	v_mfma_f32_16x16x32_bf16 v[110:113], v[36:39], v[20:23], v[110:113]
	ds_read_b128 v[32:35], v72 offset:26624
	s_waitcnt lgkmcnt(8)
	v_mfma_f32_16x16x32_bf16 v[114:117], v[40:43], v[16:19], 0
	ds_read_b128 v[36:39], v146 offset:26624
	s_waitcnt lgkmcnt(8)
	v_mfma_f32_16x16x32_bf16 v[114:117], v[44:47], v[20:23], v[114:117]
	ds_read_b128 v[40:43], v72 offset:28672
	s_waitcnt lgkmcnt(8)
	v_mfma_f32_16x16x32_bf16 v[118:121], v[48:51], v[16:19], 0
	ds_read_b128 v[44:47], v146 offset:28672
	s_waitcnt lgkmcnt(8)
	v_mfma_f32_16x16x32_bf16 v[118:121], v[52:55], v[20:23], v[118:121]
	ds_read_b128 v[48:51], v72 offset:30720
	s_waitcnt lgkmcnt(8)
	v_mfma_f32_16x16x32_bf16 v[122:125], v[56:59], v[16:19], 0
	ds_read_b128 v[52:55], v146 offset:30720
	s_waitcnt lgkmcnt(8)
	v_mfma_f32_16x16x32_bf16 v[122:125], v[60:63], v[20:23], v[122:125]
	s_waitcnt lgkmcnt(7)
	v_mfma_f32_16x16x32_bf16 v[126:129], v[64:67], v[16:19], 0
	s_waitcnt lgkmcnt(6)
	v_mfma_f32_16x16x32_bf16 v[126:129], v[68:71], v[20:23], v[126:129]
	s_waitcnt lgkmcnt(5)
	v_mfma_f32_16x16x32_bf16 v[130:133], v[32:35], v[16:19], 0
	s_waitcnt lgkmcnt(4)
	v_mfma_f32_16x16x32_bf16 v[130:133], v[36:39], v[20:23], v[130:133]
	s_waitcnt lgkmcnt(3)
	v_mfma_f32_16x16x32_bf16 v[134:137], v[40:43], v[16:19], 0
	s_waitcnt lgkmcnt(2)
	v_mfma_f32_16x16x32_bf16 v[134:137], v[44:47], v[20:23], v[134:137]
	s_waitcnt lgkmcnt(1)
	v_mfma_f32_16x16x32_bf16 v[138:141], v[48:51], v[16:19], 0
	s_waitcnt lgkmcnt(0)
	v_mfma_f32_16x16x32_bf16 v[138:141], v[52:55], v[20:23], v[138:141]
	ds_read_b64 v[48:49], v73 offset:36864
	ds_read_b64 v[50:51], v73 offset:36896
	ds_read_b64 v[52:53], v73 offset:45312
	ds_read_b64 v[54:55], v73 offset:45344
	ds_read_b64 v[56:57], v73 offset:53760
	ds_read_b64 v[58:59], v73 offset:53792
	ds_read_b64 v[60:61], v73 offset:62208
	ds_read_b64 v[62:63], v73 offset:62240
	ds_read_b64 v[64:65], v73 offset:36928
	ds_read_b64 v[66:67], v73 offset:36960
	ds_read_b64 v[68:69], v73 offset:45376
	ds_read_b64 v[70:71], v73 offset:45408
	v_max3_f32 v36, v78, v79, v80
	v_max3_f32 v36, v36, v81, v82
	v_max3_f32 v36, v36, v83, v84
	v_max3_f32 v36, v36, v85, v86
	v_max3_f32 v36, v36, v87, v88
	v_max3_f32 v36, v36, v89, v90
	v_max3_f32 v36, v36, v91, v92
	v_max3_f32 v36, v36, v93, v94
	v_max3_f32 v36, v36, v95, v96
	v_max3_f32 v36, v36, v97, v98
	v_max3_f32 v36, v36, v99, v100
	v_max3_f32 v36, v36, v101, v102
	v_max3_f32 v36, v36, v103, v104
	v_max3_f32 v36, v36, v105, v106
	v_max3_f32 v36, v36, v107, v108
	v_max3_f32 v36, v36, v109, v110
	v_max3_f32 v36, v36, v111, v112
	v_max3_f32 v36, v36, v113, v114
	v_max3_f32 v36, v36, v115, v116
	v_max3_f32 v36, v36, v117, v118
	v_max3_f32 v36, v36, v119, v120
	v_max3_f32 v36, v36, v121, v122
	v_max3_f32 v36, v36, v123, v124
	v_max3_f32 v36, v36, v125, v126
	v_max3_f32 v36, v36, v127, v128
	v_max3_f32 v36, v36, v129, v130
	v_max3_f32 v36, v36, v131, v132
	v_max3_f32 v36, v36, v133, v134
	v_max3_f32 v36, v36, v135, v136
	v_max3_f32 v36, v36, v137, v138
	v_max3_f32 v36, v36, v139, v140
	v_max_f32_e32 v36, v36, v141
	v_mov_b32_e32 v37, v36
	s_nop 1
	v_permlane16_swap_b32_e32 v36, v37
	v_max_f32_e32 v36, v36, v37
	v_mov_b32_e32 v37, v36
	s_nop 1
	v_permlane32_swap_b32_e32 v36, v37
	v_max_f32_e32 v36, v36, v37
	v_mul_f32_e64 v38, v36, -v144
	v_mov_b32_e32 v40, 0
	v_mov_b32_e32 v41, 0
	v_mov_b32_e32 v39, v38
	v_fma_f32 v78, v78, v144, v38
	v_fma_f32 v79, v79, v144, v38
	v_fma_f32 v80, v80, v144, v38
	v_fma_f32 v81, v81, v144, v38
	v_exp_f32_e32 v78, v78
	v_exp_f32_e32 v79, v79
	v_exp_f32_e32 v80, v80
	v_exp_f32_e32 v81, v81
	v_fma_f32 v82, v82, v144, v38
	v_fma_f32 v83, v83, v144, v38
	v_fma_f32 v84, v84, v144, v38
	v_fma_f32 v85, v85, v144, v38
	v_exp_f32_e32 v82, v82
	v_exp_f32_e32 v83, v83
	v_exp_f32_e32 v84, v84
	v_exp_f32_e32 v85, v85
	v_add_f32_e32 v40, v40, v78
	v_add_f32_e32 v41, v41, v79
	v_add_f32_e32 v40, v40, v80
	v_add_f32_e32 v41, v41, v81
	v_fma_f32 v86, v86, v144, v38
	v_fma_f32 v87, v87, v144, v38
	v_fma_f32 v88, v88, v144, v38
	v_fma_f32 v89, v89, v144, v38
	v_exp_f32_e32 v86, v86
	v_exp_f32_e32 v87, v87
	v_exp_f32_e32 v88, v88
	v_exp_f32_e32 v89, v89
	v_add_f32_e32 v40, v40, v82
	v_add_f32_e32 v41, v41, v83
	v_add_f32_e32 v40, v40, v84
	v_add_f32_e32 v41, v41, v85
	v_fma_f32 v90, v90, v144, v38
	v_fma_f32 v91, v91, v144, v38
	v_fma_f32 v92, v92, v144, v38
	v_fma_f32 v93, v93, v144, v38
	v_exp_f32_e32 v90, v90
	v_exp_f32_e32 v91, v91
	v_exp_f32_e32 v92, v92
	v_exp_f32_e32 v93, v93
	v_add_f32_e32 v40, v40, v86
	v_add_f32_e32 v41, v41, v87
	v_add_f32_e32 v40, v40, v88
	v_add_f32_e32 v41, v41, v89
	v_fma_f32 v94, v94, v144, v38
	v_fma_f32 v95, v95, v144, v38
	v_fma_f32 v96, v96, v144, v38
	v_fma_f32 v97, v97, v144, v38
	v_exp_f32_e32 v94, v94
	v_exp_f32_e32 v95, v95
	v_exp_f32_e32 v96, v96
	v_exp_f32_e32 v97, v97
	v_add_f32_e32 v40, v40, v90
	v_add_f32_e32 v41, v41, v91
	v_add_f32_e32 v40, v40, v92
	v_add_f32_e32 v41, v41, v93
	v_fma_f32 v98, v98, v144, v38
	v_fma_f32 v99, v99, v144, v38
	v_fma_f32 v100, v100, v144, v38
	v_fma_f32 v101, v101, v144, v38
	v_exp_f32_e32 v98, v98
	v_exp_f32_e32 v99, v99
	v_exp_f32_e32 v100, v100
	v_exp_f32_e32 v101, v101
	v_add_f32_e32 v40, v40, v94
	v_add_f32_e32 v41, v41, v95
	v_add_f32_e32 v40, v40, v96
	v_add_f32_e32 v41, v41, v97
	v_fma_f32 v102, v102, v144, v38
	v_fma_f32 v103, v103, v144, v38
	v_fma_f32 v104, v104, v144, v38
	v_fma_f32 v105, v105, v144, v38
	v_exp_f32_e32 v102, v102
	v_exp_f32_e32 v103, v103
	v_exp_f32_e32 v104, v104
	v_exp_f32_e32 v105, v105
	v_add_f32_e32 v40, v40, v98
	v_add_f32_e32 v41, v41, v99
	v_add_f32_e32 v40, v40, v100
	v_add_f32_e32 v41, v41, v101
	v_fma_f32 v106, v106, v144, v38
	v_fma_f32 v107, v107, v144, v38
	v_fma_f32 v108, v108, v144, v38
	v_fma_f32 v109, v109, v144, v38
	v_exp_f32_e32 v106, v106
	v_exp_f32_e32 v107, v107
	v_exp_f32_e32 v108, v108
	v_exp_f32_e32 v109, v109
	v_add_f32_e32 v40, v40, v102
	v_add_f32_e32 v41, v41, v103
	v_add_f32_e32 v40, v40, v104
	v_add_f32_e32 v41, v41, v105
	v_fma_f32 v110, v110, v144, v38
	v_fma_f32 v111, v111, v144, v38
	v_fma_f32 v112, v112, v144, v38
	v_fma_f32 v113, v113, v144, v38
	v_exp_f32_e32 v110, v110
	v_exp_f32_e32 v111, v111
	v_exp_f32_e32 v112, v112
	v_exp_f32_e32 v113, v113
	v_add_f32_e32 v40, v40, v106
	v_add_f32_e32 v41, v41, v107
	v_add_f32_e32 v40, v40, v108
	v_add_f32_e32 v41, v41, v109
	v_fma_f32 v114, v114, v144, v38
	v_fma_f32 v115, v115, v144, v38
	v_fma_f32 v116, v116, v144, v38
	v_fma_f32 v117, v117, v144, v38
	v_exp_f32_e32 v114, v114
	v_exp_f32_e32 v115, v115
	v_exp_f32_e32 v116, v116
	v_exp_f32_e32 v117, v117
	v_add_f32_e32 v40, v40, v110
	v_add_f32_e32 v41, v41, v111
	v_add_f32_e32 v40, v40, v112
	v_add_f32_e32 v41, v41, v113
	v_fma_f32 v118, v118, v144, v38
	v_fma_f32 v119, v119, v144, v38
	v_fma_f32 v120, v120, v144, v38
	v_fma_f32 v121, v121, v144, v38
	v_exp_f32_e32 v118, v118
	v_exp_f32_e32 v119, v119
	v_exp_f32_e32 v120, v120
	v_exp_f32_e32 v121, v121
	v_add_f32_e32 v40, v40, v114
	v_add_f32_e32 v41, v41, v115
	v_add_f32_e32 v40, v40, v116
	v_add_f32_e32 v41, v41, v117
	v_fma_f32 v122, v122, v144, v38
	v_fma_f32 v123, v123, v144, v38
	v_fma_f32 v124, v124, v144, v38
	v_fma_f32 v125, v125, v144, v38
	v_exp_f32_e32 v122, v122
	v_exp_f32_e32 v123, v123
	v_exp_f32_e32 v124, v124
	v_exp_f32_e32 v125, v125
	v_add_f32_e32 v40, v40, v118
	v_add_f32_e32 v41, v41, v119
	v_add_f32_e32 v40, v40, v120
	v_add_f32_e32 v41, v41, v121
	v_fma_f32 v126, v126, v144, v38
	v_fma_f32 v127, v127, v144, v38
	v_fma_f32 v128, v128, v144, v38
	v_fma_f32 v129, v129, v144, v38
	v_exp_f32_e32 v126, v126
	v_exp_f32_e32 v127, v127
	v_exp_f32_e32 v128, v128
	v_exp_f32_e32 v129, v129
	v_add_f32_e32 v40, v40, v122
	v_add_f32_e32 v41, v41, v123
	v_add_f32_e32 v40, v40, v124
	v_add_f32_e32 v41, v41, v125
	v_fma_f32 v130, v130, v144, v38
	v_fma_f32 v131, v131, v144, v38
	v_fma_f32 v132, v132, v144, v38
	v_fma_f32 v133, v133, v144, v38
	v_exp_f32_e32 v130, v130
	v_exp_f32_e32 v131, v131
	v_exp_f32_e32 v132, v132
	v_exp_f32_e32 v133, v133
	v_add_f32_e32 v40, v40, v126
	v_add_f32_e32 v41, v41, v127
	v_add_f32_e32 v40, v40, v128
	v_add_f32_e32 v41, v41, v129
	v_fma_f32 v134, v134, v144, v38
	v_fma_f32 v135, v135, v144, v38
	v_fma_f32 v136, v136, v144, v38
	v_fma_f32 v137, v137, v144, v38
	v_exp_f32_e32 v134, v134
	v_exp_f32_e32 v135, v135
	v_exp_f32_e32 v136, v136
	v_exp_f32_e32 v137, v137
	v_add_f32_e32 v40, v40, v130
	v_add_f32_e32 v41, v41, v131
	v_add_f32_e32 v40, v40, v132
	v_add_f32_e32 v41, v41, v133
	v_fma_f32 v138, v138, v144, v38
	v_fma_f32 v139, v139, v144, v38
	v_fma_f32 v140, v140, v144, v38
	v_fma_f32 v141, v141, v144, v38
	v_exp_f32_e32 v138, v138
	v_exp_f32_e32 v139, v139
	v_exp_f32_e32 v140, v140
	v_exp_f32_e32 v141, v141
	v_add_f32_e32 v40, v40, v134
	v_add_f32_e32 v41, v41, v135
	v_add_f32_e32 v40, v40, v136
	v_add_f32_e32 v41, v41, v137
	s_nop 0
	v_add_f32_e32 v40, v40, v138
	v_add_f32_e32 v41, v41, v139
	v_add_f32_e32 v40, v40, v140
	v_add_f32_e32 v41, v41, v141
	v_add_f32_e32 v36, v40, v41
	v_mov_b32_e32 v37, v36
	s_nop 1
	v_permlane16_swap_b32_e32 v36, v37
	v_add_f32_e32 v36, v36, v37
	v_mov_b32_e32 v37, v36
	s_nop 1
	v_permlane32_swap_b32_e32 v36, v37
	v_add_f32_e32 v36, v36, v37
	v_rcp_f32_e32 v142, v36
	v_cvt_pk_bf16_f32 v78, v78, v79
	v_cvt_pk_bf16_f32 v79, v80, v81
	v_cvt_pk_bf16_f32 v80, v82, v83
	v_cvt_pk_bf16_f32 v81, v84, v85
	v_cvt_pk_bf16_f32 v86, v86, v87
	v_cvt_pk_bf16_f32 v87, v88, v89
	v_cvt_pk_bf16_f32 v88, v90, v91
	v_cvt_pk_bf16_f32 v89, v92, v93
	v_cvt_pk_bf16_f32 v94, v94, v95
	v_cvt_pk_bf16_f32 v95, v96, v97
	v_cvt_pk_bf16_f32 v96, v98, v99
	v_cvt_pk_bf16_f32 v97, v100, v101
	v_cvt_pk_bf16_f32 v102, v102, v103
	v_cvt_pk_bf16_f32 v103, v104, v105
	v_cvt_pk_bf16_f32 v104, v106, v107
	v_cvt_pk_bf16_f32 v105, v108, v109
	v_cvt_pk_bf16_f32 v110, v110, v111
	v_cvt_pk_bf16_f32 v111, v112, v113
	v_cvt_pk_bf16_f32 v112, v114, v115
	v_cvt_pk_bf16_f32 v113, v116, v117
	v_cvt_pk_bf16_f32 v118, v118, v119
	v_cvt_pk_bf16_f32 v119, v120, v121
	v_cvt_pk_bf16_f32 v120, v122, v123
	v_cvt_pk_bf16_f32 v121, v124, v125
	v_cvt_pk_bf16_f32 v126, v126, v127
	v_cvt_pk_bf16_f32 v127, v128, v129
	v_cvt_pk_bf16_f32 v128, v130, v131
	v_cvt_pk_bf16_f32 v129, v132, v133
	v_cvt_pk_bf16_f32 v134, v134, v135
	v_cvt_pk_bf16_f32 v135, v136, v137
	v_cvt_pk_bf16_f32 v136, v138, v139
	v_cvt_pk_bf16_f32 v137, v140, v141
	v_fma_f32 v143, -v36, v142, 1.0
	v_fma_f32 v142, v143, v142, v142
	v_mov_b32_e32 v143, v142
	ds_read_b64 v[82:83], v73 offset:53824
	ds_read_b64 v[84:85], v73 offset:53856
	s_waitcnt lgkmcnt(12)
	v_mfma_f32_16x16x32_bf16 v[32:35], v[48:51], v[78:81], 0
	ds_read_b64 v[90:91], v73 offset:62272
	ds_read_b64 v[92:93], v73 offset:62304
	s_waitcnt lgkmcnt(12)
	v_mfma_f32_16x16x32_bf16 v[36:39], v[52:55], v[78:81], 0
	ds_read_b64 v[48:49], v73 offset:36992
	ds_read_b64 v[50:51], v73 offset:37024
	s_waitcnt lgkmcnt(12)
	v_mfma_f32_16x16x32_bf16 v[40:43], v[56:59], v[78:81], 0
	ds_read_b64 v[52:53], v73 offset:45440
	ds_read_b64 v[54:55], v73 offset:45472
	s_waitcnt lgkmcnt(12)
	v_mfma_f32_16x16x32_bf16 v[44:47], v[60:63], v[78:81], 0
	ds_read_b64 v[56:57], v73 offset:53888
	ds_read_b64 v[58:59], v73 offset:53920
	s_waitcnt lgkmcnt(12)
	v_mfma_f32_16x16x32_bf16 v[32:35], v[64:67], v[86:89], v[32:35]
	ds_read_b64 v[60:61], v73 offset:62336
	ds_read_b64 v[62:63], v73 offset:62368
	s_waitcnt lgkmcnt(12)
	v_mfma_f32_16x16x32_bf16 v[36:39], v[68:71], v[86:89], v[36:39]
	ds_read_b64 v[64:65], v73 offset:37056
	ds_read_b64 v[66:67], v73 offset:37088
	s_waitcnt lgkmcnt(12)
	v_mfma_f32_16x16x32_bf16 v[40:43], v[82:85], v[86:89], v[40:43]
	ds_read_b64 v[68:69], v73 offset:45504
	ds_read_b64 v[70:71], v73 offset:45536
	s_waitcnt lgkmcnt(12)
	v_mfma_f32_16x16x32_bf16 v[44:47], v[90:93], v[86:89], v[44:47]
	ds_read_b64 v[82:83], v73 offset:53952
	ds_read_b64 v[84:85], v73 offset:53984
	s_waitcnt lgkmcnt(12)
	v_mfma_f32_16x16x32_bf16 v[32:35], v[48:51], v[94:97], v[32:35]
	ds_read_b64 v[90:91], v73 offset:62400
	ds_read_b64 v[92:93], v73 offset:62432
	s_waitcnt lgkmcnt(12)
	v_mfma_f32_16x16x32_bf16 v[36:39], v[52:55], v[94:97], v[36:39]
	ds_read_b64 v[48:49], v73 offset:37120
	ds_read_b64 v[50:51], v73 offset:37152
	s_waitcnt lgkmcnt(12)
	v_mfma_f32_16x16x32_bf16 v[40:43], v[56:59], v[94:97], v[40:43]
	ds_read_b64 v[52:53], v73 offset:45568
	ds_read_b64 v[54:55], v73 offset:45600
	s_waitcnt lgkmcnt(12)
	v_mfma_f32_16x16x32_bf16 v[44:47], v[60:63], v[94:97], v[44:47]
	ds_read_b64 v[56:57], v73 offset:54016
	ds_read_b64 v[58:59], v73 offset:54048
	s_waitcnt lgkmcnt(12)
	v_mfma_f32_16x16x32_bf16 v[32:35], v[64:67], v[102:105], v[32:35]
	ds_read_b64 v[60:61], v73 offset:62464
	ds_read_b64 v[62:63], v73 offset:62496
	s_waitcnt lgkmcnt(12)
	v_mfma_f32_16x16x32_bf16 v[36:39], v[68:71], v[102:105], v[36:39]
	ds_read_b64 v[64:65], v73 offset:37184
	ds_read_b64 v[66:67], v73 offset:37216
	s_waitcnt lgkmcnt(12)
	v_mfma_f32_16x16x32_bf16 v[40:43], v[82:85], v[102:105], v[40:43]
	ds_read_b64 v[68:69], v73 offset:45632
	ds_read_b64 v[70:71], v73 offset:45664
	s_waitcnt lgkmcnt(12)
	v_mfma_f32_16x16x32_bf16 v[44:47], v[90:93], v[102:105], v[44:47]
	ds_read_b64 v[82:83], v73 offset:54080
	ds_read_b64 v[84:85], v73 offset:54112
	s_waitcnt lgkmcnt(12)
	v_mfma_f32_16x16x32_bf16 v[32:35], v[48:51], v[110:113], v[32:35]
	ds_read_b64 v[90:91], v73 offset:62528
	ds_read_b64 v[92:93], v73 offset:62560
	s_waitcnt lgkmcnt(12)
	v_mfma_f32_16x16x32_bf16 v[36:39], v[52:55], v[110:113], v[36:39]
	ds_read_b64 v[48:49], v73 offset:37248
	ds_read_b64 v[50:51], v73 offset:37280
	s_waitcnt lgkmcnt(12)
	v_mfma_f32_16x16x32_bf16 v[40:43], v[56:59], v[110:113], v[40:43]
	ds_read_b64 v[52:53], v73 offset:45696
	ds_read_b64 v[54:55], v73 offset:45728
	s_waitcnt lgkmcnt(12)
	v_mfma_f32_16x16x32_bf16 v[44:47], v[60:63], v[110:113], v[44:47]
	ds_read_b64 v[56:57], v73 offset:54144
	ds_read_b64 v[58:59], v73 offset:54176
	s_waitcnt lgkmcnt(12)
	v_mfma_f32_16x16x32_bf16 v[32:35], v[64:67], v[118:121], v[32:35]
	ds_read_b64 v[60:61], v73 offset:62592
	ds_read_b64 v[62:63], v73 offset:62624
	s_waitcnt lgkmcnt(12)
	v_mfma_f32_16x16x32_bf16 v[36:39], v[68:71], v[118:121], v[36:39]
	ds_read_b64 v[64:65], v73 offset:37312
	ds_read_b64 v[66:67], v73 offset:37344
	s_waitcnt lgkmcnt(12)
	v_mfma_f32_16x16x32_bf16 v[40:43], v[82:85], v[118:121], v[40:43]
	ds_read_b64 v[68:69], v73 offset:45760
	ds_read_b64 v[70:71], v73 offset:45792
	s_waitcnt lgkmcnt(12)
	v_mfma_f32_16x16x32_bf16 v[44:47], v[90:93], v[118:121], v[44:47]
	ds_read_b64 v[82:83], v73 offset:54208
	ds_read_b64 v[84:85], v73 offset:54240
	s_waitcnt lgkmcnt(12)
	v_mfma_f32_16x16x32_bf16 v[32:35], v[48:51], v[126:129], v[32:35]
	ds_read_b64 v[90:91], v73 offset:62656
	ds_read_b64 v[92:93], v73 offset:62688
	s_waitcnt lgkmcnt(12)
	v_mfma_f32_16x16x32_bf16 v[36:39], v[52:55], v[126:129], v[36:39]
	s_waitcnt lgkmcnt(10)
	v_mfma_f32_16x16x32_bf16 v[40:43], v[56:59], v[126:129], v[40:43]
	s_waitcnt lgkmcnt(8)
	v_mfma_f32_16x16x32_bf16 v[44:47], v[60:63], v[126:129], v[44:47]
	s_waitcnt lgkmcnt(6)
	v_mfma_f32_16x16x32_bf16 v[32:35], v[64:67], v[134:137], v[32:35]
	s_waitcnt lgkmcnt(4)
	v_mfma_f32_16x16x32_bf16 v[36:39], v[68:71], v[134:137], v[36:39]
	s_waitcnt lgkmcnt(2)
	v_mfma_f32_16x16x32_bf16 v[40:43], v[82:85], v[134:137], v[40:43]
	s_waitcnt lgkmcnt(0)
	v_mfma_f32_16x16x32_bf16 v[44:47], v[90:93], v[134:137], v[44:47]
	ds_read_b128 v[48:51], v72 offset:0
	ds_read_b128 v[52:55], v146 offset:0
	ds_read_b128 v[56:59], v72 offset:2048
	ds_read_b128 v[60:63], v146 offset:2048
	ds_read_b128 v[64:67], v72 offset:4096
	ds_read_b128 v[68:71], v146 offset:4096
	s_add_u32 s16, s12, 0x80000
	s_addc_u32 s17, s13, 0
	s_nop 7
	v_mul_f32_e32 v32, v32, v142
	v_mul_f32_e32 v33, v33, v142
	v_mul_f32_e32 v34, v34, v142
	v_mul_f32_e32 v35, v35, v142
	v_mul_f32_e32 v36, v36, v142
	v_mul_f32_e32 v37, v37, v142
	v_mul_f32_e32 v38, v38, v142
	v_mul_f32_e32 v39, v39, v142
	v_mul_f32_e32 v40, v40, v142
	v_mul_f32_e32 v41, v41, v142
	v_mul_f32_e32 v42, v42, v142
	v_mul_f32_e32 v43, v43, v142
	v_mul_f32_e32 v44, v44, v142
	v_mul_f32_e32 v45, v45, v142
	v_mul_f32_e32 v46, v46, v142
	v_mul_f32_e32 v47, v47, v142
	v_cvt_pk_bf16_f32 v32, v32, v33
	v_cvt_pk_bf16_f32 v33, v34, v35
	v_cvt_pk_bf16_f32 v36, v36, v37
	v_cvt_pk_bf16_f32 v37, v38, v39
	v_cvt_pk_bf16_f32 v40, v40, v41
	v_cvt_pk_bf16_f32 v41, v42, v43
	v_cvt_pk_bf16_f32 v44, v44, v45
	v_cvt_pk_bf16_f32 v45, v46, v47
	global_store_dwordx2 v74, v[32:33], s[16:17] offset:0
	global_store_dwordx2 v74, v[36:37], s[16:17] offset:32
	global_store_dwordx2 v74, v[40:41], s[16:17] offset:64
	global_store_dwordx2 v74, v[44:45], s[16:17] offset:96
	ds_read_b128 v[32:35], v72 offset:6144
	ds_read_b128 v[36:39], v146 offset:6144
	ds_read_b128 v[40:43], v72 offset:8192
	s_waitcnt lgkmcnt(8)
	v_mfma_f32_16x16x32_bf16 v[78:81], v[48:51], v[24:27], 0
	ds_read_b128 v[44:47], v146 offset:8192
	s_waitcnt lgkmcnt(8)
	v_mfma_f32_16x16x32_bf16 v[78:81], v[52:55], v[28:31], v[78:81]
	ds_read_b128 v[48:51], v72 offset:10240
	s_waitcnt lgkmcnt(8)
	v_mfma_f32_16x16x32_bf16 v[82:85], v[56:59], v[24:27], 0
	ds_read_b128 v[52:55], v146 offset:10240
	s_waitcnt lgkmcnt(8)
	v_mfma_f32_16x16x32_bf16 v[82:85], v[60:63], v[28:31], v[82:85]
	ds_read_b128 v[56:59], v72 offset:12288
	s_waitcnt lgkmcnt(8)
	v_mfma_f32_16x16x32_bf16 v[86:89], v[64:67], v[24:27], 0
	ds_read_b128 v[60:63], v146 offset:12288
	s_waitcnt lgkmcnt(8)
	v_mfma_f32_16x16x32_bf16 v[86:89], v[68:71], v[28:31], v[86:89]
	ds_read_b128 v[64:67], v72 offset:14336
	s_waitcnt lgkmcnt(8)
	v_mfma_f32_16x16x32_bf16 v[90:93], v[32:35], v[24:27], 0
	ds_read_b128 v[68:71], v146 offset:14336
	s_waitcnt lgkmcnt(8)
	v_mfma_f32_16x16x32_bf16 v[90:93], v[36:39], v[28:31], v[90:93]
	ds_read_b128 v[32:35], v72 offset:16384
	s_waitcnt lgkmcnt(8)
	v_mfma_f32_16x16x32_bf16 v[94:97], v[40:43], v[24:27], 0
	ds_read_b128 v[36:39], v146 offset:16384
	s_waitcnt lgkmcnt(8)
	v_mfma_f32_16x16x32_bf16 v[94:97], v[44:47], v[28:31], v[94:97]
	ds_read_b128 v[40:43], v72 offset:18432
	s_waitcnt lgkmcnt(8)
	v_mfma_f32_16x16x32_bf16 v[98:101], v[48:51], v[24:27], 0
	ds_read_b128 v[44:47], v146 offset:18432
	s_waitcnt lgkmcnt(8)
	v_mfma_f32_16x16x32_bf16 v[98:101], v[52:55], v[28:31], v[98:101]
	ds_read_b128 v[48:51], v72 offset:20480
	s_waitcnt lgkmcnt(8)
	v_mfma_f32_16x16x32_bf16 v[102:105], v[56:59], v[24:27], 0
	ds_read_b128 v[52:55], v146 offset:20480
	s_waitcnt lgkmcnt(8)
	v_mfma_f32_16x16x32_bf16 v[102:105], v[60:63], v[28:31], v[102:105]
	ds_read_b128 v[56:59], v72 offset:22528
	s_waitcnt lgkmcnt(8)
	v_mfma_f32_16x16x32_bf16 v[106:109], v[64:67], v[24:27], 0
	ds_read_b128 v[60:63], v146 offset:22528
	s_waitcnt lgkmcnt(8)
	v_mfma_f32_16x16x32_bf16 v[106:109], v[68:71], v[28:31], v[106:109]
	ds_read_b128 v[64:67], v72 offset:24576
	s_waitcnt lgkmcnt(8)
	v_mfma_f32_16x16x32_bf16 v[110:113], v[32:35], v[24:27], 0
	ds_read_b128 v[68:71], v146 offset:24576
	s_waitcnt lgkmcnt(8)
	v_mfma_f32_16x16x32_bf16 v[110:113], v[36:39], v[28:31], v[110:113]
	ds_read_b128 v[32:35], v72 offset:26624
	s_waitcnt lgkmcnt(8)
	v_mfma_f32_16x16x32_bf16 v[114:117], v[40:43], v[24:27], 0
	ds_read_b128 v[36:39], v146 offset:26624
	s_waitcnt lgkmcnt(8)
	v_mfma_f32_16x16x32_bf16 v[114:117], v[44:47], v[28:31], v[114:117]
	ds_read_b128 v[40:43], v72 offset:28672
	s_waitcnt lgkmcnt(8)
	v_mfma_f32_16x16x32_bf16 v[118:121], v[48:51], v[24:27], 0
	ds_read_b128 v[44:47], v146 offset:28672
	s_waitcnt lgkmcnt(8)
	v_mfma_f32_16x16x32_bf16 v[118:121], v[52:55], v[28:31], v[118:121]
	ds_read_b128 v[48:51], v72 offset:30720
	s_waitcnt lgkmcnt(8)
	v_mfma_f32_16x16x32_bf16 v[122:125], v[56:59], v[24:27], 0
	ds_read_b128 v[52:55], v146 offset:30720
	s_waitcnt lgkmcnt(8)
	v_mfma_f32_16x16x32_bf16 v[122:125], v[60:63], v[28:31], v[122:125]
	s_waitcnt lgkmcnt(7)
	v_mfma_f32_16x16x32_bf16 v[126:129], v[64:67], v[24:27], 0
	s_waitcnt lgkmcnt(6)
	v_mfma_f32_16x16x32_bf16 v[126:129], v[68:71], v[28:31], v[126:129]
	s_waitcnt lgkmcnt(5)
	v_mfma_f32_16x16x32_bf16 v[130:133], v[32:35], v[24:27], 0
	s_waitcnt lgkmcnt(4)
	v_mfma_f32_16x16x32_bf16 v[130:133], v[36:39], v[28:31], v[130:133]
	s_waitcnt lgkmcnt(3)
	v_mfma_f32_16x16x32_bf16 v[134:137], v[40:43], v[24:27], 0
	s_waitcnt lgkmcnt(2)
	v_mfma_f32_16x16x32_bf16 v[134:137], v[44:47], v[28:31], v[134:137]
	s_waitcnt lgkmcnt(1)
	v_mfma_f32_16x16x32_bf16 v[138:141], v[48:51], v[24:27], 0
	s_waitcnt lgkmcnt(0)
	v_mfma_f32_16x16x32_bf16 v[138:141], v[52:55], v[28:31], v[138:141]
	ds_read_b64 v[48:49], v73 offset:36864
	ds_read_b64 v[50:51], v73 offset:36896
	ds_read_b64 v[52:53], v73 offset:45312
	ds_read_b64 v[54:55], v73 offset:45344
	ds_read_b64 v[56:57], v73 offset:53760
	ds_read_b64 v[58:59], v73 offset:53792
	ds_read_b64 v[60:61], v73 offset:62208
	ds_read_b64 v[62:63], v73 offset:62240
	ds_read_b64 v[64:65], v73 offset:36928
	ds_read_b64 v[66:67], v73 offset:36960
	ds_read_b64 v[68:69], v73 offset:45376
	ds_read_b64 v[70:71], v73 offset:45408
	v_max3_f32 v36, v78, v79, v80
	v_max3_f32 v36, v36, v81, v82
	v_max3_f32 v36, v36, v83, v84
	v_max3_f32 v36, v36, v85, v86
	v_max3_f32 v36, v36, v87, v88
	v_max3_f32 v36, v36, v89, v90
	v_max3_f32 v36, v36, v91, v92
	v_max3_f32 v36, v36, v93, v94
	v_max3_f32 v36, v36, v95, v96
	v_max3_f32 v36, v36, v97, v98
	v_max3_f32 v36, v36, v99, v100
	v_max3_f32 v36, v36, v101, v102
	v_max3_f32 v36, v36, v103, v104
	v_max3_f32 v36, v36, v105, v106
	v_max3_f32 v36, v36, v107, v108
	v_max3_f32 v36, v36, v109, v110
	v_max3_f32 v36, v36, v111, v112
	v_max3_f32 v36, v36, v113, v114
	v_max3_f32 v36, v36, v115, v116
	v_max3_f32 v36, v36, v117, v118
	v_max3_f32 v36, v36, v119, v120
	v_max3_f32 v36, v36, v121, v122
	v_max3_f32 v36, v36, v123, v124
	v_max3_f32 v36, v36, v125, v126
	v_max3_f32 v36, v36, v127, v128
	v_max3_f32 v36, v36, v129, v130
	v_max3_f32 v36, v36, v131, v132
	v_max3_f32 v36, v36, v133, v134
	v_max3_f32 v36, v36, v135, v136
	v_max3_f32 v36, v36, v137, v138
	v_max3_f32 v36, v36, v139, v140
	v_max_f32_e32 v36, v36, v141
	v_mov_b32_e32 v37, v36
	s_nop 1
	v_permlane16_swap_b32_e32 v36, v37
	v_max_f32_e32 v36, v36, v37
	v_mov_b32_e32 v37, v36
	s_nop 1
	v_permlane32_swap_b32_e32 v36, v37
	v_max_f32_e32 v36, v36, v37
	v_mul_f32_e64 v38, v36, -v144
	v_mov_b32_e32 v40, 0
	v_mov_b32_e32 v41, 0
	v_mov_b32_e32 v39, v38
	v_fma_f32 v78, v78, v144, v38
	v_fma_f32 v79, v79, v144, v38
	v_fma_f32 v80, v80, v144, v38
	v_fma_f32 v81, v81, v144, v38
	v_exp_f32_e32 v78, v78
	v_exp_f32_e32 v79, v79
	v_exp_f32_e32 v80, v80
	v_exp_f32_e32 v81, v81
	v_fma_f32 v82, v82, v144, v38
	v_fma_f32 v83, v83, v144, v38
	v_fma_f32 v84, v84, v144, v38
	v_fma_f32 v85, v85, v144, v38
	v_exp_f32_e32 v82, v82
	v_exp_f32_e32 v83, v83
	v_exp_f32_e32 v84, v84
	v_exp_f32_e32 v85, v85
	v_add_f32_e32 v40, v40, v78
	v_add_f32_e32 v41, v41, v79
	v_add_f32_e32 v40, v40, v80
	v_add_f32_e32 v41, v41, v81
	v_fma_f32 v86, v86, v144, v38
	v_fma_f32 v87, v87, v144, v38
	v_fma_f32 v88, v88, v144, v38
	v_fma_f32 v89, v89, v144, v38
	v_exp_f32_e32 v86, v86
	v_exp_f32_e32 v87, v87
	v_exp_f32_e32 v88, v88
	v_exp_f32_e32 v89, v89
	v_add_f32_e32 v40, v40, v82
	v_add_f32_e32 v41, v41, v83
	v_add_f32_e32 v40, v40, v84
	v_add_f32_e32 v41, v41, v85
	v_fma_f32 v90, v90, v144, v38
	v_fma_f32 v91, v91, v144, v38
	v_fma_f32 v92, v92, v144, v38
	v_fma_f32 v93, v93, v144, v38
	v_exp_f32_e32 v90, v90
	v_exp_f32_e32 v91, v91
	v_exp_f32_e32 v92, v92
	v_exp_f32_e32 v93, v93
	v_add_f32_e32 v40, v40, v86
	v_add_f32_e32 v41, v41, v87
	v_add_f32_e32 v40, v40, v88
	v_add_f32_e32 v41, v41, v89
	v_fma_f32 v94, v94, v144, v38
	v_fma_f32 v95, v95, v144, v38
	v_fma_f32 v96, v96, v144, v38
	v_fma_f32 v97, v97, v144, v38
	v_exp_f32_e32 v94, v94
	v_exp_f32_e32 v95, v95
	v_exp_f32_e32 v96, v96
	v_exp_f32_e32 v97, v97
	v_add_f32_e32 v40, v40, v90
	v_add_f32_e32 v41, v41, v91
	v_add_f32_e32 v40, v40, v92
	v_add_f32_e32 v41, v41, v93
	v_fma_f32 v98, v98, v144, v38
	v_fma_f32 v99, v99, v144, v38
	v_fma_f32 v100, v100, v144, v38
	v_fma_f32 v101, v101, v144, v38
	v_exp_f32_e32 v98, v98
	v_exp_f32_e32 v99, v99
	v_exp_f32_e32 v100, v100
	v_exp_f32_e32 v101, v101
	v_add_f32_e32 v40, v40, v94
	v_add_f32_e32 v41, v41, v95
	v_add_f32_e32 v40, v40, v96
	v_add_f32_e32 v41, v41, v97
	v_fma_f32 v102, v102, v144, v38
	v_fma_f32 v103, v103, v144, v38
	v_fma_f32 v104, v104, v144, v38
	v_fma_f32 v105, v105, v144, v38
	v_exp_f32_e32 v102, v102
	v_exp_f32_e32 v103, v103
	v_exp_f32_e32 v104, v104
	v_exp_f32_e32 v105, v105
	v_add_f32_e32 v40, v40, v98
	v_add_f32_e32 v41, v41, v99
	v_add_f32_e32 v40, v40, v100
	v_add_f32_e32 v41, v41, v101
	v_fma_f32 v106, v106, v144, v38
	v_fma_f32 v107, v107, v144, v38
	v_fma_f32 v108, v108, v144, v38
	v_fma_f32 v109, v109, v144, v38
	v_exp_f32_e32 v106, v106
	v_exp_f32_e32 v107, v107
	v_exp_f32_e32 v108, v108
	v_exp_f32_e32 v109, v109
	v_add_f32_e32 v40, v40, v102
	v_add_f32_e32 v41, v41, v103
	v_add_f32_e32 v40, v40, v104
	v_add_f32_e32 v41, v41, v105
	v_fma_f32 v110, v110, v144, v38
	v_fma_f32 v111, v111, v144, v38
	v_fma_f32 v112, v112, v144, v38
	v_fma_f32 v113, v113, v144, v38
	v_exp_f32_e32 v110, v110
	v_exp_f32_e32 v111, v111
	v_exp_f32_e32 v112, v112
	v_exp_f32_e32 v113, v113
	v_add_f32_e32 v40, v40, v106
	v_add_f32_e32 v41, v41, v107
	v_add_f32_e32 v40, v40, v108
	v_add_f32_e32 v41, v41, v109
	v_fma_f32 v114, v114, v144, v38
	v_fma_f32 v115, v115, v144, v38
	v_fma_f32 v116, v116, v144, v38
	v_fma_f32 v117, v117, v144, v38
	v_exp_f32_e32 v114, v114
	v_exp_f32_e32 v115, v115
	v_exp_f32_e32 v116, v116
	v_exp_f32_e32 v117, v117
	v_add_f32_e32 v40, v40, v110
	v_add_f32_e32 v41, v41, v111
	v_add_f32_e32 v40, v40, v112
	v_add_f32_e32 v41, v41, v113
	v_fma_f32 v118, v118, v144, v38
	v_fma_f32 v119, v119, v144, v38
	v_fma_f32 v120, v120, v144, v38
	v_fma_f32 v121, v121, v144, v38
	v_exp_f32_e32 v118, v118
	v_exp_f32_e32 v119, v119
	v_exp_f32_e32 v120, v120
	v_exp_f32_e32 v121, v121
	v_add_f32_e32 v40, v40, v114
	v_add_f32_e32 v41, v41, v115
	v_add_f32_e32 v40, v40, v116
	v_add_f32_e32 v41, v41, v117
	v_fma_f32 v122, v122, v144, v38
	v_fma_f32 v123, v123, v144, v38
	v_fma_f32 v124, v124, v144, v38
	v_fma_f32 v125, v125, v144, v38
	v_exp_f32_e32 v122, v122
	v_exp_f32_e32 v123, v123
	v_exp_f32_e32 v124, v124
	v_exp_f32_e32 v125, v125
	v_add_f32_e32 v40, v40, v118
	v_add_f32_e32 v41, v41, v119
	v_add_f32_e32 v40, v40, v120
	v_add_f32_e32 v41, v41, v121
	v_fma_f32 v126, v126, v144, v38
	v_fma_f32 v127, v127, v144, v38
	v_fma_f32 v128, v128, v144, v38
	v_fma_f32 v129, v129, v144, v38
	v_exp_f32_e32 v126, v126
	v_exp_f32_e32 v127, v127
	v_exp_f32_e32 v128, v128
	v_exp_f32_e32 v129, v129
	v_add_f32_e32 v40, v40, v122
	v_add_f32_e32 v41, v41, v123
	v_add_f32_e32 v40, v40, v124
	v_add_f32_e32 v41, v41, v125
	v_fma_f32 v130, v130, v144, v38
	v_fma_f32 v131, v131, v144, v38
	v_fma_f32 v132, v132, v144, v38
	v_fma_f32 v133, v133, v144, v38
	v_exp_f32_e32 v130, v130
	v_exp_f32_e32 v131, v131
	v_exp_f32_e32 v132, v132
	v_exp_f32_e32 v133, v133
	v_add_f32_e32 v40, v40, v126
	v_add_f32_e32 v41, v41, v127
	v_add_f32_e32 v40, v40, v128
	v_add_f32_e32 v41, v41, v129
	v_fma_f32 v134, v134, v144, v38
	v_fma_f32 v135, v135, v144, v38
	v_fma_f32 v136, v136, v144, v38
	v_fma_f32 v137, v137, v144, v38
	v_exp_f32_e32 v134, v134
	v_exp_f32_e32 v135, v135
	v_exp_f32_e32 v136, v136
	v_exp_f32_e32 v137, v137
	v_add_f32_e32 v40, v40, v130
	v_add_f32_e32 v41, v41, v131
	v_add_f32_e32 v40, v40, v132
	v_add_f32_e32 v41, v41, v133
	v_fma_f32 v138, v138, v144, v38
	v_fma_f32 v139, v139, v144, v38
	v_fma_f32 v140, v140, v144, v38
	v_fma_f32 v141, v141, v144, v38
	v_exp_f32_e32 v138, v138
	v_exp_f32_e32 v139, v139
	v_exp_f32_e32 v140, v140
	v_exp_f32_e32 v141, v141
	v_add_f32_e32 v40, v40, v134
	v_add_f32_e32 v41, v41, v135
	v_add_f32_e32 v40, v40, v136
	v_add_f32_e32 v41, v41, v137
	s_nop 0
	v_add_f32_e32 v40, v40, v138
	v_add_f32_e32 v41, v41, v139
	v_add_f32_e32 v40, v40, v140
	v_add_f32_e32 v41, v41, v141
	v_add_f32_e32 v36, v40, v41
	v_mov_b32_e32 v37, v36
	s_nop 1
	v_permlane16_swap_b32_e32 v36, v37
	v_add_f32_e32 v36, v36, v37
	v_mov_b32_e32 v37, v36
	s_nop 1
	v_permlane32_swap_b32_e32 v36, v37
	v_add_f32_e32 v36, v36, v37
	v_rcp_f32_e32 v142, v36
	v_cvt_pk_bf16_f32 v78, v78, v79
	v_cvt_pk_bf16_f32 v79, v80, v81
	v_cvt_pk_bf16_f32 v80, v82, v83
	v_cvt_pk_bf16_f32 v81, v84, v85
	v_cvt_pk_bf16_f32 v86, v86, v87
	v_cvt_pk_bf16_f32 v87, v88, v89
	v_cvt_pk_bf16_f32 v88, v90, v91
	v_cvt_pk_bf16_f32 v89, v92, v93
	v_cvt_pk_bf16_f32 v94, v94, v95
	v_cvt_pk_bf16_f32 v95, v96, v97
	v_cvt_pk_bf16_f32 v96, v98, v99
	v_cvt_pk_bf16_f32 v97, v100, v101
	v_cvt_pk_bf16_f32 v102, v102, v103
	v_cvt_pk_bf16_f32 v103, v104, v105
	v_cvt_pk_bf16_f32 v104, v106, v107
	v_cvt_pk_bf16_f32 v105, v108, v109
	v_cvt_pk_bf16_f32 v110, v110, v111
	v_cvt_pk_bf16_f32 v111, v112, v113
	v_cvt_pk_bf16_f32 v112, v114, v115
	v_cvt_pk_bf16_f32 v113, v116, v117
	v_cvt_pk_bf16_f32 v118, v118, v119
	v_cvt_pk_bf16_f32 v119, v120, v121
	v_cvt_pk_bf16_f32 v120, v122, v123
	v_cvt_pk_bf16_f32 v121, v124, v125
	v_cvt_pk_bf16_f32 v126, v126, v127
	v_cvt_pk_bf16_f32 v127, v128, v129
	v_cvt_pk_bf16_f32 v128, v130, v131
	v_cvt_pk_bf16_f32 v129, v132, v133
	v_cvt_pk_bf16_f32 v134, v134, v135
	v_cvt_pk_bf16_f32 v135, v136, v137
	v_cvt_pk_bf16_f32 v136, v138, v139
	v_cvt_pk_bf16_f32 v137, v140, v141
	v_fma_f32 v143, -v36, v142, 1.0
	v_fma_f32 v142, v143, v142, v142
	v_mov_b32_e32 v143, v142
	ds_read_b64 v[82:83], v73 offset:53824
	ds_read_b64 v[84:85], v73 offset:53856
	s_waitcnt lgkmcnt(12)
	v_mfma_f32_16x16x32_bf16 v[32:35], v[48:51], v[78:81], 0
	ds_read_b64 v[90:91], v73 offset:62272
	ds_read_b64 v[92:93], v73 offset:62304
	s_waitcnt lgkmcnt(12)
	v_mfma_f32_16x16x32_bf16 v[36:39], v[52:55], v[78:81], 0
	ds_read_b64 v[48:49], v73 offset:36992
	ds_read_b64 v[50:51], v73 offset:37024
	s_waitcnt lgkmcnt(12)
	v_mfma_f32_16x16x32_bf16 v[40:43], v[56:59], v[78:81], 0
	ds_read_b64 v[52:53], v73 offset:45440
	ds_read_b64 v[54:55], v73 offset:45472
	s_waitcnt lgkmcnt(12)
	v_mfma_f32_16x16x32_bf16 v[44:47], v[60:63], v[78:81], 0
	ds_read_b64 v[56:57], v73 offset:53888
	ds_read_b64 v[58:59], v73 offset:53920
	s_waitcnt lgkmcnt(12)
	v_mfma_f32_16x16x32_bf16 v[32:35], v[64:67], v[86:89], v[32:35]
	ds_read_b64 v[60:61], v73 offset:62336
	ds_read_b64 v[62:63], v73 offset:62368
	s_waitcnt lgkmcnt(12)
	v_mfma_f32_16x16x32_bf16 v[36:39], v[68:71], v[86:89], v[36:39]
	ds_read_b64 v[64:65], v73 offset:37056
	ds_read_b64 v[66:67], v73 offset:37088
	s_waitcnt lgkmcnt(12)
	v_mfma_f32_16x16x32_bf16 v[40:43], v[82:85], v[86:89], v[40:43]
	ds_read_b64 v[68:69], v73 offset:45504
	ds_read_b64 v[70:71], v73 offset:45536
	s_waitcnt lgkmcnt(12)
	v_mfma_f32_16x16x32_bf16 v[44:47], v[90:93], v[86:89], v[44:47]
	ds_read_b64 v[82:83], v73 offset:53952
	ds_read_b64 v[84:85], v73 offset:53984
	s_waitcnt lgkmcnt(12)
	v_mfma_f32_16x16x32_bf16 v[32:35], v[48:51], v[94:97], v[32:35]
	ds_read_b64 v[90:91], v73 offset:62400
	ds_read_b64 v[92:93], v73 offset:62432
	s_waitcnt lgkmcnt(12)
	v_mfma_f32_16x16x32_bf16 v[36:39], v[52:55], v[94:97], v[36:39]
	ds_read_b64 v[48:49], v73 offset:37120
	ds_read_b64 v[50:51], v73 offset:37152
	s_waitcnt lgkmcnt(12)
	v_mfma_f32_16x16x32_bf16 v[40:43], v[56:59], v[94:97], v[40:43]
	ds_read_b64 v[52:53], v73 offset:45568
	ds_read_b64 v[54:55], v73 offset:45600
	s_waitcnt lgkmcnt(12)
	v_mfma_f32_16x16x32_bf16 v[44:47], v[60:63], v[94:97], v[44:47]
	ds_read_b64 v[56:57], v73 offset:54016
	ds_read_b64 v[58:59], v73 offset:54048
	s_waitcnt lgkmcnt(12)
	v_mfma_f32_16x16x32_bf16 v[32:35], v[64:67], v[102:105], v[32:35]
	ds_read_b64 v[60:61], v73 offset:62464
	ds_read_b64 v[62:63], v73 offset:62496
	s_waitcnt lgkmcnt(12)
	v_mfma_f32_16x16x32_bf16 v[36:39], v[68:71], v[102:105], v[36:39]
	ds_read_b64 v[64:65], v73 offset:37184
	ds_read_b64 v[66:67], v73 offset:37216
	s_waitcnt lgkmcnt(12)
	v_mfma_f32_16x16x32_bf16 v[40:43], v[82:85], v[102:105], v[40:43]
	ds_read_b64 v[68:69], v73 offset:45632
	ds_read_b64 v[70:71], v73 offset:45664
	s_waitcnt lgkmcnt(12)
	v_mfma_f32_16x16x32_bf16 v[44:47], v[90:93], v[102:105], v[44:47]
	ds_read_b64 v[82:83], v73 offset:54080
	ds_read_b64 v[84:85], v73 offset:54112
	s_waitcnt lgkmcnt(12)
	v_mfma_f32_16x16x32_bf16 v[32:35], v[48:51], v[110:113], v[32:35]
	ds_read_b64 v[90:91], v73 offset:62528
	ds_read_b64 v[92:93], v73 offset:62560
	s_waitcnt lgkmcnt(12)
	v_mfma_f32_16x16x32_bf16 v[36:39], v[52:55], v[110:113], v[36:39]
	ds_read_b64 v[48:49], v73 offset:37248
	ds_read_b64 v[50:51], v73 offset:37280
	s_waitcnt lgkmcnt(12)
	v_mfma_f32_16x16x32_bf16 v[40:43], v[56:59], v[110:113], v[40:43]
	ds_read_b64 v[52:53], v73 offset:45696
	ds_read_b64 v[54:55], v73 offset:45728
	s_waitcnt lgkmcnt(12)
	v_mfma_f32_16x16x32_bf16 v[44:47], v[60:63], v[110:113], v[44:47]
	ds_read_b64 v[56:57], v73 offset:54144
	ds_read_b64 v[58:59], v73 offset:54176
	s_waitcnt lgkmcnt(12)
	v_mfma_f32_16x16x32_bf16 v[32:35], v[64:67], v[118:121], v[32:35]
	ds_read_b64 v[60:61], v73 offset:62592
	ds_read_b64 v[62:63], v73 offset:62624
	s_waitcnt lgkmcnt(12)
	v_mfma_f32_16x16x32_bf16 v[36:39], v[68:71], v[118:121], v[36:39]
	ds_read_b64 v[64:65], v73 offset:37312
	ds_read_b64 v[66:67], v73 offset:37344
	s_waitcnt lgkmcnt(12)
	v_mfma_f32_16x16x32_bf16 v[40:43], v[82:85], v[118:121], v[40:43]
	ds_read_b64 v[68:69], v73 offset:45760
	ds_read_b64 v[70:71], v73 offset:45792
	s_waitcnt lgkmcnt(12)
	v_mfma_f32_16x16x32_bf16 v[44:47], v[90:93], v[118:121], v[44:47]
	ds_read_b64 v[82:83], v73 offset:54208
	ds_read_b64 v[84:85], v73 offset:54240
	s_waitcnt lgkmcnt(12)
	v_mfma_f32_16x16x32_bf16 v[32:35], v[48:51], v[126:129], v[32:35]
	ds_read_b64 v[90:91], v73 offset:62656
	ds_read_b64 v[92:93], v73 offset:62688
	s_waitcnt lgkmcnt(12)
	v_mfma_f32_16x16x32_bf16 v[36:39], v[52:55], v[126:129], v[36:39]
	s_waitcnt lgkmcnt(10)
	v_mfma_f32_16x16x32_bf16 v[40:43], v[56:59], v[126:129], v[40:43]
	s_waitcnt lgkmcnt(8)
	v_mfma_f32_16x16x32_bf16 v[44:47], v[60:63], v[126:129], v[44:47]
	s_waitcnt lgkmcnt(6)
	v_mfma_f32_16x16x32_bf16 v[32:35], v[64:67], v[134:137], v[32:35]
	s_waitcnt lgkmcnt(4)
	v_mfma_f32_16x16x32_bf16 v[36:39], v[68:71], v[134:137], v[36:39]
	s_waitcnt lgkmcnt(2)
	v_mfma_f32_16x16x32_bf16 v[40:43], v[82:85], v[134:137], v[40:43]
	s_waitcnt lgkmcnt(0)
	v_mfma_f32_16x16x32_bf16 v[44:47], v[90:93], v[134:137], v[44:47]
	s_add_u32 s16, s12, 0x88000
	s_addc_u32 s17, s13, 0
	s_nop 7
	v_mul_f32_e32 v32, v32, v142
	v_mul_f32_e32 v33, v33, v142
	v_mul_f32_e32 v34, v34, v142
	v_mul_f32_e32 v35, v35, v142
	v_mul_f32_e32 v36, v36, v142
	v_mul_f32_e32 v37, v37, v142
	v_mul_f32_e32 v38, v38, v142
	v_mul_f32_e32 v39, v39, v142
	v_mul_f32_e32 v40, v40, v142
	v_mul_f32_e32 v41, v41, v142
	v_mul_f32_e32 v42, v42, v142
	v_mul_f32_e32 v43, v43, v142
	v_mul_f32_e32 v44, v44, v142
	v_mul_f32_e32 v45, v45, v142
	v_mul_f32_e32 v46, v46, v142
	v_mul_f32_e32 v47, v47, v142
	v_cvt_pk_bf16_f32 v32, v32, v33
	v_cvt_pk_bf16_f32 v33, v34, v35
	v_cvt_pk_bf16_f32 v36, v36, v37
	v_cvt_pk_bf16_f32 v37, v38, v39
	v_cvt_pk_bf16_f32 v40, v40, v41
	v_cvt_pk_bf16_f32 v41, v42, v43
	v_cvt_pk_bf16_f32 v44, v44, v45
	v_cvt_pk_bf16_f32 v45, v46, v47
	global_store_dwordx2 v74, v[32:33], s[16:17] offset:0
	global_store_dwordx2 v74, v[36:37], s[16:17] offset:32
	global_store_dwordx2 v74, v[40:41], s[16:17] offset:64
	global_store_dwordx2 v74, v[44:45], s[16:17] offset:96
	s_cmp_eq_u32 m0, 0x1234
	s_cbranch_scc1 .Latt_late_ret
	s_branch .LBB0_270
